# up/down K-loops: the 4 per-iteration v_add_u32 rebuilding the ds_read base addresses replaced by 4 loop-invariant address registers set once per tile (on top of the saddr-form DMA addresses)
# speedup vs baseline: 1.0114x; 1.0024x over previous
; #define PG8_STAGE(bufoff, gbase, voff) do { _Pragma("unroll") for (int _i = 0; _i < 2; ++_i) \
;         __builtin_amdgcn_global_load_lds((const unsigned*)((const char*)(gbase) + (voff)[_i]), (PG8_LAS unsigned*)(lds + (bufoff) + ldsw + _i * 8192), 16, 0, 0); } while (0)
; #define PG8_LDA(dst, b, h) do { _Pragma("unroll") for (int m = 0; m < 4; ++m) _Pragma("unroll") for (int k = 0; k < 2; ++k) dst[m][k] = *(const PG8_LAS bf16x8*)(lds + PG8_SA(b, h) + aoff + m * 2048 + k * 1024); } while (0)
; #define PG8_LDB(dst, b, h) do { _Pragma("unroll") for (int n = 0; n < 2; ++n) _Pragma("unroll") for (int k = 0; k < 2; ++k) dst[n][k] = *(const PG8_LAS bf16x8*)(lds + PG8_SB(b, h) + boff + n * 2048 + k * 1024); } while (0)
; #define PG8_WAIT_V(n) asm volatile("s_waitcnt vmcnt(" #n ")" ::: "memory")
; #define PG8_WAIT_L(n) asm volatile("s_waitcnt lgkmcnt(" #n ")" ::: "memory")
; #define PG8_BAR __builtin_amdgcn_s_barrier()
; template <class Epi, class Sched, bool ALIGN_EPI = false, bool SP2 = false>
; __device__ __forceinline__ void gemm_phase(PG8_LAS unsigned char* lds, const Gemm g, const Sched& S, const Epi& E, int wave_s) {
;     ...
;         const bool has_next = S.next(ui + 1, nxt);
;         const char* nA = has_next ? (const char*)g.A + (size_t)nxt.pm * tstepA + (size_t)(nxt.pn / g.npg) * (size_t)(K * 2) : cA; const char* nB = has_next ? (const char*)g.Bt + (size_t)nxt.pn * tstepB : cB;
;         for (int t = 0; t < nt; t += 2) {
;             const bool last = (t == nt - 2);
;             const char* a1 = cA + (size_t)(t + 1) * kstep;
;             const char* a2 = last ? nA : cA + (size_t)(t + 2) * kstep; const char* b2 = last ? nB : cB + (size_t)(t + 2) * kstep;
;             const char* a3 = a2 + kstep; const char* b3 = b2 + kstep;
;             if (last && has_next) S.a_ready(nxt);
;             if constexpr (SP2) {
;             PG8_LDB(B0, 0, 0); PG8_LDB(B1, 0, 1); PG8_SCHED; PG8_LDA(At, 0, 0); PG8_STAGE(PG8_SA(1, 1), a1 + hstepA, voffA);
;             PG8_WAIT_V(8); PG8_WAIT_L(0); PG8_BAR; PG8_MMA(0, 0, At, B0); PG8_MMA(0, 1, At, B1); PG8_BAR; PG8_SCHED;
;             PG8_LDA(At, 0, 1); PG8_STAGE(PG8_SB(0, 0), b2, voffB); PG8_STAGE(PG8_SB(0, 1), b2 + hstepB, voffB); PG8_STAGE(PG8_SA(0, 0), a2, voffA);
;             PG8_WAIT_V(8); PG8_WAIT_L(0); PG8_BAR; PG8_MMA(1, 0, At, B0); PG8_MMA(1, 1, At, B1); PG8_BAR; PG8_SCHED;
.LBB0_690:
	v_add_u32_e32 v228, 0x10000, v251
	v_add_u32_e32 v229, 0x14000, v251
	v_add_u32_e32 v230, 0x18000, v251
	v_add_u32_e32 v231, 0x1c000, v251
	s_ashr_i32 s89, s88, 31
	s_lshl_b64 s[2:3], s[88:89], 20
	s_add_u32 s28, s22, s2
	s_addc_u32 s29, s23, s3
	s_and_b64 s[2:3], s[4:5], exec
	s_cselect_b32 s2, s29, s41
	s_cselect_b32 s3, s28, s40
	s_add_u32 s89, s40, 0x100
	s_addc_u32 s91, s41, 0
	s_mov_b32 vcc_lo, -2
	s_add_u32 s4, s30, 0x100
	s_addc_u32 s5, s31, 0
	s_add_i32 vcc_hi, 0, 0x10000
	s_cmp_eq_u32 vcc_lo, 28
	s_cselect_b32 s41, s21, s5
	s_cselect_b32 s40, s20, s4
	s_cselect_b32 s7, s2, s91
	s_cselect_b32 s6, s3, s89
	s_add_i32 s86, 0, 0x14000
	ds_read_b128 v[126:129], v228
	ds_read_b128 v[134:137], v228 offset:1024
	ds_read_b128 v[138:141], v228 offset:2048
	ds_read_b128 v[142:145], v228 offset:3072
	ds_read_b128 v[146:149], v229
	ds_read_b128 v[150:153], v229 offset:1024
	ds_read_b128 v[154:157], v229 offset:2048
	ds_read_b128 v[158:161], v229 offset:3072
	s_add_i32 m0, s36, 0xc000
	ds_read_b128 v[162:165], v252
	ds_read_b128 v[166:169], v252 offset:1024
	ds_read_b128 v[170:173], v252 offset:2048
	ds_read_b128 v[174:177], v252 offset:3072
	ds_read_b128 v[178:181], v252 offset:4096
	ds_read_b128 v[182:185], v252 offset:5120
	ds_read_b128 v[186:189], v252 offset:6144
	ds_read_b128 v[190:193], v252 offset:7168
	global_load_lds_dwordx4 v244, s[30:31]
	s_add_i32 m0, s36, 0xe000
	s_nop 0
	global_load_lds_dwordx4 v246, s[30:31]
	s_waitcnt vmcnt(8)
	s_waitcnt lgkmcnt(0)
	s_barrier
	s_waitcnt lgkmcnt(0)
	v_mfma_f32_16x16x32_bf16 v[130:133], v[126:129], v[162:165], 0
	v_mfma_f32_16x16x32_bf16 v[118:121], v[138:141], v[162:165], 0
	v_mfma_f32_16x16x32_bf16 v[110:113], v[126:129], v[170:173], 0
	v_mfma_f32_16x16x32_bf16 v[98:101], v[138:141], v[170:173], 0
	v_mfma_f32_16x16x32_bf16 v[62:65], v[126:129], v[178:181], 0
	v_mfma_f32_16x16x32_bf16 v[58:61], v[138:141], v[178:181], 0
	v_mfma_f32_16x16x32_bf16 v[46:49], v[126:129], v[186:189], 0
	v_mfma_f32_16x16x32_bf16 v[42:45], v[138:141], v[186:189], 0
	v_mfma_f32_16x16x32_bf16 v[130:133], v[134:137], v[166:169], v[130:133]
	v_mfma_f32_16x16x32_bf16 v[118:121], v[142:145], v[166:169], v[118:121]
	v_mfma_f32_16x16x32_bf16 v[110:113], v[134:137], v[174:177], v[110:113]
	v_mfma_f32_16x16x32_bf16 v[98:101], v[142:145], v[174:177], v[98:101]
	v_mfma_f32_16x16x32_bf16 v[62:65], v[134:137], v[182:185], v[62:65]
	v_mfma_f32_16x16x32_bf16 v[58:61], v[142:145], v[182:185], v[58:61]
	v_mfma_f32_16x16x32_bf16 v[46:49], v[134:137], v[190:193], v[46:49]
	v_mfma_f32_16x16x32_bf16 v[42:45], v[142:145], v[190:193], v[42:45]
	v_mfma_f32_16x16x32_bf16 v[102:105], v[146:149], v[162:165], 0
	v_mfma_f32_16x16x32_bf16 v[74:77], v[154:157], v[162:165], 0
	v_mfma_f32_16x16x32_bf16 v[78:81], v[146:149], v[170:173], 0
	v_mfma_f32_16x16x32_bf16 v[90:93], v[154:157], v[170:173], 0
	v_mfma_f32_16x16x32_bf16 v[34:37], v[146:149], v[178:181], 0
	v_mfma_f32_16x16x32_bf16 v[26:29], v[154:157], v[178:181], 0
	v_mfma_f32_16x16x32_bf16 v[14:17], v[146:149], v[186:189], 0
	v_mfma_f32_16x16x32_bf16 v[2:5], v[154:157], v[186:189], 0
	v_mfma_f32_16x16x32_bf16 v[102:105], v[150:153], v[166:169], v[102:105]
	v_mfma_f32_16x16x32_bf16 v[74:77], v[158:161], v[166:169], v[74:77]
	v_mfma_f32_16x16x32_bf16 v[78:81], v[150:153], v[174:177], v[78:81]
	v_mfma_f32_16x16x32_bf16 v[90:93], v[158:161], v[174:177], v[90:93]
	v_mfma_f32_16x16x32_bf16 v[34:37], v[150:153], v[182:185], v[34:37]
	v_mfma_f32_16x16x32_bf16 v[26:29], v[158:161], v[182:185], v[26:29]
	v_mfma_f32_16x16x32_bf16 v[14:17], v[150:153], v[190:193], v[14:17]
	v_mfma_f32_16x16x32_bf16 v[2:5], v[158:161], v[190:193], v[2:5]
	s_barrier
	s_add_i32 s30, vcc_hi, s35
	v_lshl_add_u64 v[194:195], s[6:7], 0, v[238:239]
	s_mov_b32 m0, s30
	ds_read_b128 v[162:165], v252 offset:16384
	ds_read_b128 v[166:169], v252 offset:17408
	ds_read_b128 v[170:173], v252 offset:18432
	ds_read_b128 v[174:177], v252 offset:19456
	ds_read_b128 v[178:181], v252 offset:20480
	ds_read_b128 v[182:185], v252 offset:21504
	ds_read_b128 v[186:189], v252 offset:22528
	ds_read_b128 v[190:193], v252 offset:23552
	global_load_lds_dwordx4 v[194:195], off
	s_add_i32 m0, s30, 0x2000
	s_add_u32 s30, s6, 0x80000
	v_lshl_add_u64 v[196:197], s[6:7], 0, v[242:243]
	s_addc_u32 s31, s7, 0
	s_add_i32 s86, s86, s35
	global_load_lds_dwordx4 v[196:197], off
	s_mov_b32 m0, s86
	v_lshl_add_u64 v[200:201], s[40:41], 0, v[240:241]
	global_load_lds_dwordx4 v238, s[30:31]
	s_add_i32 m0, s86, 0x2000
	s_nop 0
	global_load_lds_dwordx4 v242, s[30:31]
	v_lshl_add_u64 v[198:199], s[40:41], 0, v[236:237]
	s_mov_b32 m0, s36
	s_nop 0
	global_load_lds_dwordx4 v[198:199], off
	s_mov_b32 m0, s37
	s_nop 0
	global_load_lds_dwordx4 v[200:201], off
	s_waitcnt vmcnt(8)
	s_waitcnt lgkmcnt(0)
	s_barrier
; #define PG8_STAGE(bufoff, gbase, voff) do { _Pragma("unroll") for (int _i = 0; _i < 2; ++_i) \
;         __builtin_amdgcn_global_load_lds((const unsigned*)((const char*)(gbase) + (voff)[_i]), (PG8_LAS unsigned*)(lds + (bufoff) + ldsw + _i * 8192), 16, 0, 0); } while (0)
; #define PG8_LDA(dst, b, h) do { _Pragma("unroll") for (int m = 0; m < 4; ++m) _Pragma("unroll") for (int k = 0; k < 2; ++k) dst[m][k] = *(const PG8_LAS bf16x8*)(lds + PG8_SA(b, h) + aoff + m * 2048 + k * 1024); } while (0)
; #define PG8_LDB(dst, b, h) do { _Pragma("unroll") for (int n = 0; n < 2; ++n) _Pragma("unroll") for (int k = 0; k < 2; ++k) dst[n][k] = *(const PG8_LAS bf16x8*)(lds + PG8_SB(b, h) + boff + n * 2048 + k * 1024); } while (0)
; #define PG8_MMA(ai, bj, At, Bt) do { __builtin_amdgcn_s_setprio(1); _Pragma("unroll") for (int m = 0; m < 4; ++m) _Pragma("unroll") for (int n = 0; n < 2; ++n) _Pragma("unroll") for (int k = 0; k < 2; ++k) \
;         acc[ai][bj][m][n] = __builtin_amdgcn_mfma_f32_16x16x32_bf16(Bt[n][k], At[m][k], acc[ai][bj][m][n], 0, 0, 0); __builtin_amdgcn_s_setprio(0); } while (0)
; #define PG8_WAIT_V(n) asm volatile("s_waitcnt vmcnt(" #n ")" ::: "memory")
; #define PG8_WAIT_L(n) asm volatile("s_waitcnt lgkmcnt(" #n ")" ::: "memory")
; #define PG8_BAR __builtin_amdgcn_s_barrier()
; #define PG8_SCHED __builtin_amdgcn_sched_barrier(0)
; template <class Epi, class Sched, bool ALIGN_EPI = false, bool SP2 = false>
; __device__ __forceinline__ void gemm_phase(PG8_LAS unsigned char* lds, const Gemm g, const Sched& S, const Epi& E, int wave_s) {
;     ...
;             PG8_WAIT_V(8); PG8_WAIT_L(0); PG8_BAR; PG8_MMA(0, 0, At, B0); PG8_MMA(0, 1, At, B1); PG8_BAR; PG8_SCHED;
;             PG8_LDA(At, 0, 1); PG8_STAGE(PG8_SB(0, 0), b2, voffB); PG8_STAGE(PG8_SB(0, 1), b2 + hstepB, voffB); PG8_STAGE(PG8_SA(0, 0), a2, voffA);
;             PG8_WAIT_V(8); PG8_WAIT_L(0); PG8_BAR; PG8_MMA(1, 0, At, B0); PG8_MMA(1, 1, At, B1); PG8_BAR; PG8_SCHED;
;             PG8_LDB(B0, 1, 0); PG8_LDB(B1, 1, 1); PG8_SCHED; PG8_LDA(At, 1, 0); PG8_STAGE(PG8_SA(0, 1), a2 + hstepA, voffA);
;             PG8_WAIT_V(8); PG8_WAIT_L(0); PG8_BAR; PG8_MMA(0, 0, At, B0); PG8_MMA(0, 1, At, B1); PG8_BAR; PG8_SCHED;
	s_waitcnt lgkmcnt(0)
	v_mfma_f32_16x16x32_bf16 v[54:57], v[126:129], v[162:165], 0
	v_mfma_f32_16x16x32_bf16 v[50:53], v[138:141], v[162:165], 0
	v_mfma_f32_16x16x32_bf16 v[38:41], v[126:129], v[170:173], 0
	v_mfma_f32_16x16x32_bf16 v[30:33], v[138:141], v[170:173], 0
	v_mfma_f32_16x16x32_bf16 v[86:89], v[126:129], v[178:181], 0
	v_mfma_f32_16x16x32_bf16 v[122:125], v[138:141], v[178:181], 0
	v_mfma_f32_16x16x32_bf16 v[114:117], v[126:129], v[186:189], 0
	v_mfma_f32_16x16x32_bf16 v[106:109], v[138:141], v[186:189], 0
	v_mfma_f32_16x16x32_bf16 v[54:57], v[134:137], v[166:169], v[54:57]
	v_mfma_f32_16x16x32_bf16 v[50:53], v[142:145], v[166:169], v[50:53]
	v_mfma_f32_16x16x32_bf16 v[38:41], v[134:137], v[174:177], v[38:41]
	v_mfma_f32_16x16x32_bf16 v[30:33], v[142:145], v[174:177], v[30:33]
	v_mfma_f32_16x16x32_bf16 v[86:89], v[134:137], v[182:185], v[86:89]
	v_mfma_f32_16x16x32_bf16 v[122:125], v[142:145], v[182:185], v[122:125]
	v_mfma_f32_16x16x32_bf16 v[114:117], v[134:137], v[190:193], v[114:117]
	v_mfma_f32_16x16x32_bf16 v[106:109], v[142:145], v[190:193], v[106:109]
	v_mfma_f32_16x16x32_bf16 v[22:25], v[146:149], v[162:165], 0
	v_mfma_f32_16x16x32_bf16 v[18:21], v[154:157], v[162:165], 0
	v_mfma_f32_16x16x32_bf16 v[10:13], v[146:149], v[170:173], 0
	v_mfma_f32_16x16x32_bf16 v[6:9], v[154:157], v[170:173], 0
	v_mfma_f32_16x16x32_bf16 v[82:85], v[146:149], v[178:181], 0
	v_mfma_f32_16x16x32_bf16 v[94:97], v[154:157], v[178:181], 0
	v_mfma_f32_16x16x32_bf16 v[70:73], v[146:149], v[186:189], 0
	v_mfma_f32_16x16x32_bf16 v[66:69], v[154:157], v[186:189], 0
	v_mfma_f32_16x16x32_bf16 v[22:25], v[150:153], v[166:169], v[22:25]
	v_mfma_f32_16x16x32_bf16 v[18:21], v[158:161], v[166:169], v[18:21]
	v_mfma_f32_16x16x32_bf16 v[10:13], v[150:153], v[174:177], v[10:13]
	v_mfma_f32_16x16x32_bf16 v[6:9], v[158:161], v[174:177], v[6:9]
	v_mfma_f32_16x16x32_bf16 v[82:85], v[150:153], v[182:185], v[82:85]
	v_mfma_f32_16x16x32_bf16 v[94:97], v[158:161], v[182:185], v[94:97]
	v_mfma_f32_16x16x32_bf16 v[70:73], v[150:153], v[190:193], v[70:73]
	v_mfma_f32_16x16x32_bf16 v[66:69], v[158:161], v[190:193], v[66:69]
	s_barrier
	s_add_i32 s86, 0, 0x18000
	s_add_i32 s87, 0, 0x1c000
	ds_read_b128 v[126:129], v230
	ds_read_b128 v[134:137], v230 offset:1024
	ds_read_b128 v[138:141], v230 offset:2048
	ds_read_b128 v[142:145], v230 offset:3072
	ds_read_b128 v[146:149], v231
	ds_read_b128 v[150:153], v231 offset:1024
	ds_read_b128 v[154:157], v231 offset:2048
	ds_read_b128 v[158:161], v231 offset:3072
	s_add_u32 s30, s40, 0x4000
	s_addc_u32 s31, s41, 0
	s_mov_b32 m0, s42
	ds_read_b128 v[162:165], v252 offset:32768
	ds_read_b128 v[166:169], v252 offset:33792
	ds_read_b128 v[170:173], v252 offset:34816
	ds_read_b128 v[174:177], v252 offset:35840
	ds_read_b128 v[178:181], v252 offset:36864
	ds_read_b128 v[182:185], v252 offset:37888
	ds_read_b128 v[186:189], v252 offset:38912
	ds_read_b128 v[190:193], v252 offset:39936
	global_load_lds_dwordx4 v236, s[30:31]
	s_mov_b32 m0, s43
	s_nop 0
	global_load_lds_dwordx4 v240, s[30:31]
	s_waitcnt vmcnt(8)
	s_waitcnt lgkmcnt(0)
	s_barrier
	s_waitcnt lgkmcnt(0)
	v_mfma_f32_16x16x32_bf16 v[130:133], v[126:129], v[162:165], v[130:133]
	v_mfma_f32_16x16x32_bf16 v[118:121], v[138:141], v[162:165], v[118:121]
	v_mfma_f32_16x16x32_bf16 v[110:113], v[126:129], v[170:173], v[110:113]
	v_mfma_f32_16x16x32_bf16 v[98:101], v[138:141], v[170:173], v[98:101]
	v_mfma_f32_16x16x32_bf16 v[62:65], v[126:129], v[178:181], v[62:65]
	v_mfma_f32_16x16x32_bf16 v[58:61], v[138:141], v[178:181], v[58:61]
	v_mfma_f32_16x16x32_bf16 v[46:49], v[126:129], v[186:189], v[46:49]
	v_mfma_f32_16x16x32_bf16 v[42:45], v[138:141], v[186:189], v[42:45]
	v_mfma_f32_16x16x32_bf16 v[130:133], v[134:137], v[166:169], v[130:133]
	v_mfma_f32_16x16x32_bf16 v[118:121], v[142:145], v[166:169], v[118:121]
	v_mfma_f32_16x16x32_bf16 v[110:113], v[134:137], v[174:177], v[110:113]
	v_mfma_f32_16x16x32_bf16 v[98:101], v[142:145], v[174:177], v[98:101]
	v_mfma_f32_16x16x32_bf16 v[62:65], v[134:137], v[182:185], v[62:65]
	v_mfma_f32_16x16x32_bf16 v[58:61], v[142:145], v[182:185], v[58:61]
	v_mfma_f32_16x16x32_bf16 v[46:49], v[134:137], v[190:193], v[46:49]
	v_mfma_f32_16x16x32_bf16 v[42:45], v[142:145], v[190:193], v[42:45]
	v_mfma_f32_16x16x32_bf16 v[102:105], v[146:149], v[162:165], v[102:105]
	v_mfma_f32_16x16x32_bf16 v[74:77], v[154:157], v[162:165], v[74:77]
	v_mfma_f32_16x16x32_bf16 v[78:81], v[146:149], v[170:173], v[78:81]
	v_mfma_f32_16x16x32_bf16 v[90:93], v[154:157], v[170:173], v[90:93]
	v_mfma_f32_16x16x32_bf16 v[34:37], v[146:149], v[178:181], v[34:37]
	v_mfma_f32_16x16x32_bf16 v[26:29], v[154:157], v[178:181], v[26:29]
	v_mfma_f32_16x16x32_bf16 v[14:17], v[146:149], v[186:189], v[14:17]
	v_mfma_f32_16x16x32_bf16 v[2:5], v[154:157], v[186:189], v[2:5]
	v_mfma_f32_16x16x32_bf16 v[102:105], v[150:153], v[166:169], v[102:105]
	v_mfma_f32_16x16x32_bf16 v[74:77], v[158:161], v[166:169], v[74:77]
	v_mfma_f32_16x16x32_bf16 v[78:81], v[150:153], v[174:177], v[78:81]
	v_mfma_f32_16x16x32_bf16 v[90:93], v[158:161], v[174:177], v[90:93]
	v_mfma_f32_16x16x32_bf16 v[34:37], v[150:153], v[182:185], v[34:37]
	v_mfma_f32_16x16x32_bf16 v[26:29], v[158:161], v[182:185], v[26:29]
	v_mfma_f32_16x16x32_bf16 v[14:17], v[150:153], v[190:193], v[14:17]
	v_mfma_f32_16x16x32_bf16 v[2:5], v[158:161], v[190:193], v[2:5]
	s_barrier
; #define PG8_STAGE(bufoff, gbase, voff) do { _Pragma("unroll") for (int _i = 0; _i < 2; ++_i) \
;         __builtin_amdgcn_global_load_lds((const unsigned*)((const char*)(gbase) + (voff)[_i]), (PG8_LAS unsigned*)(lds + (bufoff) + ldsw + _i * 8192), 16, 0, 0); } while (0)
; #define PG8_LDA(dst, b, h) do { _Pragma("unroll") for (int m = 0; m < 4; ++m) _Pragma("unroll") for (int k = 0; k < 2; ++k) dst[m][k] = *(const PG8_LAS bf16x8*)(lds + PG8_SA(b, h) + aoff + m * 2048 + k * 1024); } while (0)
; #define PG8_LDB(dst, b, h) do { _Pragma("unroll") for (int n = 0; n < 2; ++n) _Pragma("unroll") for (int k = 0; k < 2; ++k) dst[n][k] = *(const PG8_LAS bf16x8*)(lds + PG8_SB(b, h) + boff + n * 2048 + k * 1024); } while (0)
; #define PG8_MMA(ai, bj, At, Bt) do { __builtin_amdgcn_s_setprio(1); _Pragma("unroll") for (int m = 0; m < 4; ++m) _Pragma("unroll") for (int n = 0; n < 2; ++n) _Pragma("unroll") for (int k = 0; k < 2; ++k) \
;         acc[ai][bj][m][n] = __builtin_amdgcn_mfma_f32_16x16x32_bf16(Bt[n][k], At[m][k], acc[ai][bj][m][n], 0, 0, 0); __builtin_amdgcn_s_setprio(0); } while (0)
; #define PG8_WAIT_V(n) asm volatile("s_waitcnt vmcnt(" #n ")" ::: "memory")
; #define PG8_BAR __builtin_amdgcn_s_barrier()
; template <class Epi, class Sched, bool ALIGN_EPI = false, bool SP2 = false>
; __device__ __forceinline__ void gemm_phase(PG8_LAS unsigned char* lds, const Gemm g, const Sched& S, const Epi& E, int wave_s) {
;     ...
;         for (int t = 0; t < nt; t += 2) {
;             const bool last = (t == nt - 2);
;             const char* a1 = cA + (size_t)(t + 1) * kstep;
;             const char* a2 = last ? nA : cA + (size_t)(t + 2) * kstep; const char* b2 = last ? nB : cB + (size_t)(t + 2) * kstep;
;             const char* a3 = a2 + kstep; const char* b3 = b2 + kstep;
;             if (last && has_next) S.a_ready(nxt);
;             if constexpr (SP2) {
;             PG8_LDB(B0, 0, 0); PG8_LDB(B1, 0, 1); PG8_SCHED; PG8_LDA(At, 0, 0); PG8_STAGE(PG8_SA(1, 1), a1 + hstepA, voffA);
;             PG8_WAIT_V(8); PG8_WAIT_L(0); PG8_BAR; PG8_MMA(0, 0, At, B0); PG8_MMA(0, 1, At, B1); PG8_BAR; PG8_SCHED;
;     ...
;             PG8_LDA(At, 1, 1); PG8_STAGE(PG8_SB(1, 0), b3, voffB); PG8_STAGE(PG8_SB(1, 1), b3 + hstepB, voffB); PG8_STAGE(PG8_SA(1, 0), a3, voffA);
;             PG8_WAIT_V(8); PG8_WAIT_L(0); PG8_BAR; PG8_MMA(1, 0, At, B0); PG8_MMA(1, 1, At, B1); PG8_BAR; PG8_SCHED;
	s_add_i32 s30, s86, s35
	v_lshl_add_u64 v[194:195], v[194:195], 0, s[60:61]
	s_mov_b32 m0, s30
	ds_read_b128 v[162:165], v252 offset:49152
	ds_read_b128 v[166:169], v252 offset:50176
	ds_read_b128 v[170:173], v252 offset:51200
	ds_read_b128 v[174:177], v252 offset:52224
	ds_read_b128 v[178:181], v252 offset:53248
	ds_read_b128 v[182:185], v252 offset:54272
	ds_read_b128 v[186:189], v252 offset:55296
	ds_read_b128 v[190:193], v252 offset:56320
	global_load_lds_dwordx4 v[194:195], off
	s_add_i32 m0, s30, 0x2000
	s_add_u32 s6, s6, 0x80080
	v_lshl_add_u64 v[194:195], v[196:197], 0, s[60:61]
	s_addc_u32 s7, s7, 0
	s_add_i32 s30, s87, s35
	global_load_lds_dwordx4 v[194:195], off
	s_mov_b32 m0, s30
	s_nop 0
	global_load_lds_dwordx4 v238, s[6:7]
	s_add_i32 m0, s30, 0x2000
	s_nop 0
	global_load_lds_dwordx4 v242, s[6:7]
	v_lshl_add_u64 v[194:195], v[198:199], 0, s[60:61]
	s_mov_b32 m0, s77
	s_nop 0
	global_load_lds_dwordx4 v[194:195], off
	v_lshl_add_u64 v[194:195], v[200:201], 0, s[60:61]
	s_mov_b32 m0, s94
	s_nop 0
	global_load_lds_dwordx4 v[194:195], off
	s_waitcnt vmcnt(8)
	s_waitcnt lgkmcnt(0)
	s_barrier
	s_waitcnt lgkmcnt(0)
	v_mfma_f32_16x16x32_bf16 v[54:57], v[126:129], v[162:165], v[54:57]
	v_mfma_f32_16x16x32_bf16 v[50:53], v[138:141], v[162:165], v[50:53]
	v_mfma_f32_16x16x32_bf16 v[38:41], v[126:129], v[170:173], v[38:41]
	v_mfma_f32_16x16x32_bf16 v[30:33], v[138:141], v[170:173], v[30:33]
	v_mfma_f32_16x16x32_bf16 v[86:89], v[126:129], v[178:181], v[86:89]
	v_mfma_f32_16x16x32_bf16 v[122:125], v[138:141], v[178:181], v[122:125]
	v_mfma_f32_16x16x32_bf16 v[114:117], v[126:129], v[186:189], v[114:117]
	v_mfma_f32_16x16x32_bf16 v[106:109], v[138:141], v[186:189], v[106:109]
	v_mfma_f32_16x16x32_bf16 v[54:57], v[134:137], v[166:169], v[54:57]
	v_mfma_f32_16x16x32_bf16 v[50:53], v[142:145], v[166:169], v[50:53]
	v_mfma_f32_16x16x32_bf16 v[38:41], v[134:137], v[174:177], v[38:41]
	v_mfma_f32_16x16x32_bf16 v[30:33], v[142:145], v[174:177], v[30:33]
	v_mfma_f32_16x16x32_bf16 v[86:89], v[134:137], v[182:185], v[86:89]
	v_mfma_f32_16x16x32_bf16 v[122:125], v[142:145], v[182:185], v[122:125]
	v_mfma_f32_16x16x32_bf16 v[114:117], v[134:137], v[190:193], v[114:117]
	v_mfma_f32_16x16x32_bf16 v[106:109], v[142:145], v[190:193], v[106:109]
	v_mfma_f32_16x16x32_bf16 v[22:25], v[146:149], v[162:165], v[22:25]
	v_mfma_f32_16x16x32_bf16 v[18:21], v[154:157], v[162:165], v[18:21]
	v_mfma_f32_16x16x32_bf16 v[10:13], v[146:149], v[170:173], v[10:13]
	v_mfma_f32_16x16x32_bf16 v[6:9], v[154:157], v[170:173], v[6:9]
	v_mfma_f32_16x16x32_bf16 v[82:85], v[146:149], v[178:181], v[82:85]
	v_mfma_f32_16x16x32_bf16 v[94:97], v[154:157], v[178:181], v[94:97]
	v_mfma_f32_16x16x32_bf16 v[70:73], v[146:149], v[186:189], v[70:73]
	v_mfma_f32_16x16x32_bf16 v[66:69], v[154:157], v[186:189], v[66:69]
	v_mfma_f32_16x16x32_bf16 v[22:25], v[150:153], v[166:169], v[22:25]
	v_mfma_f32_16x16x32_bf16 v[18:21], v[158:161], v[166:169], v[18:21]
	v_mfma_f32_16x16x32_bf16 v[10:13], v[150:153], v[174:177], v[10:13]
	v_mfma_f32_16x16x32_bf16 v[6:9], v[158:161], v[174:177], v[6:9]
	v_mfma_f32_16x16x32_bf16 v[82:85], v[150:153], v[182:185], v[82:85]
	v_mfma_f32_16x16x32_bf16 v[94:97], v[158:161], v[182:185], v[94:97]
	v_mfma_f32_16x16x32_bf16 v[70:73], v[150:153], v[190:193], v[70:73]
	v_mfma_f32_16x16x32_bf16 v[66:69], v[158:161], v[190:193], v[66:69]
	s_barrier
	s_add_i32 vcc_lo, vcc_lo, 2
	s_add_u32 s89, s89, 0x100
	s_addc_u32 s91, s91, 0
	s_cmp_gt_u32 vcc_lo, 29
	s_mov_b64 s[30:31], s[4:5]
.LBB0_691:
	s_add_u32 s4, s30, 0x100
	s_addc_u32 s5, s31, 0
	s_add_i32 vcc_hi, 0, 0x10000
	s_cmp_eq_u32 vcc_lo, 28
	s_cselect_b32 s41, s21, s5
	s_cselect_b32 s40, s20, s4
	s_cselect_b32 s7, s2, s91
	s_cselect_b32 s6, s3, s89
	s_add_i32 s86, 0, 0x14000
	ds_read_b128 v[126:129], v228
	ds_read_b128 v[134:137], v228 offset:1024
	ds_read_b128 v[138:141], v228 offset:2048
	ds_read_b128 v[142:145], v228 offset:3072
	ds_read_b128 v[146:149], v229
	ds_read_b128 v[150:153], v229 offset:1024
	ds_read_b128 v[154:157], v229 offset:2048
	ds_read_b128 v[158:161], v229 offset:3072
	s_add_i32 m0, s36, 0xc000
	ds_read_b128 v[162:165], v252
	ds_read_b128 v[166:169], v252 offset:1024
	ds_read_b128 v[170:173], v252 offset:2048
	ds_read_b128 v[174:177], v252 offset:3072
	ds_read_b128 v[178:181], v252 offset:4096
	ds_read_b128 v[182:185], v252 offset:5120
	ds_read_b128 v[186:189], v252 offset:6144
	ds_read_b128 v[190:193], v252 offset:7168
	global_load_lds_dwordx4 v244, s[30:31]
	s_add_i32 m0, s36, 0xe000
	s_nop 0
	global_load_lds_dwordx4 v246, s[30:31]
	s_waitcnt vmcnt(8)
	s_waitcnt lgkmcnt(0)
	s_barrier
; #define PG8_STAGE(bufoff, gbase, voff) do { _Pragma("unroll") for (int _i = 0; _i < 2; ++_i) \
;         __builtin_amdgcn_global_load_lds((const unsigned*)((const char*)(gbase) + (voff)[_i]), (PG8_LAS unsigned*)(lds + (bufoff) + ldsw + _i * 8192), 16, 0, 0); } while (0)
; #define PG8_LDA(dst, b, h) do { _Pragma("unroll") for (int m = 0; m < 4; ++m) _Pragma("unroll") for (int k = 0; k < 2; ++k) dst[m][k] = *(const PG8_LAS bf16x8*)(lds + PG8_SA(b, h) + aoff + m * 2048 + k * 1024); } while (0)
; #define PG8_LDB(dst, b, h) do { _Pragma("unroll") for (int n = 0; n < 2; ++n) _Pragma("unroll") for (int k = 0; k < 2; ++k) dst[n][k] = *(const PG8_LAS bf16x8*)(lds + PG8_SB(b, h) + boff + n * 2048 + k * 1024); } while (0)
; #define PG8_MMA(ai, bj, At, Bt) do { __builtin_amdgcn_s_setprio(1); _Pragma("unroll") for (int m = 0; m < 4; ++m) _Pragma("unroll") for (int n = 0; n < 2; ++n) _Pragma("unroll") for (int k = 0; k < 2; ++k) \
;         acc[ai][bj][m][n] = __builtin_amdgcn_mfma_f32_16x16x32_bf16(Bt[n][k], At[m][k], acc[ai][bj][m][n], 0, 0, 0); __builtin_amdgcn_s_setprio(0); } while (0)
; #define PG8_WAIT_V(n) asm volatile("s_waitcnt vmcnt(" #n ")" ::: "memory")
; #define PG8_WAIT_L(n) asm volatile("s_waitcnt lgkmcnt(" #n ")" ::: "memory")
; #define PG8_BAR __builtin_amdgcn_s_barrier()
; #define PG8_SCHED __builtin_amdgcn_sched_barrier(0)
; template <class Epi, class Sched, bool ALIGN_EPI = false, bool SP2 = false>
; __device__ __forceinline__ void gemm_phase(PG8_LAS unsigned char* lds, const Gemm g, const Sched& S, const Epi& E, int wave_s) {
;     ...
;             PG8_LDB(B0, 0, 0); PG8_LDB(B1, 0, 1); PG8_SCHED; PG8_LDA(At, 0, 0); PG8_STAGE(PG8_SA(1, 1), a1 + hstepA, voffA);
;             PG8_WAIT_V(8); PG8_WAIT_L(0); PG8_BAR; PG8_MMA(0, 0, At, B0); PG8_MMA(0, 1, At, B1); PG8_BAR; PG8_SCHED;
;             PG8_LDA(At, 0, 1); PG8_STAGE(PG8_SB(0, 0), b2, voffB); PG8_STAGE(PG8_SB(0, 1), b2 + hstepB, voffB); PG8_STAGE(PG8_SA(0, 0), a2, voffA);
;             PG8_WAIT_V(8); PG8_WAIT_L(0); PG8_BAR; PG8_MMA(1, 0, At, B0); PG8_MMA(1, 1, At, B1); PG8_BAR; PG8_SCHED;
	s_waitcnt lgkmcnt(0)
	v_mfma_f32_16x16x32_bf16 v[130:133], v[126:129], v[162:165], v[130:133]
	v_mfma_f32_16x16x32_bf16 v[118:121], v[138:141], v[162:165], v[118:121]
	v_mfma_f32_16x16x32_bf16 v[110:113], v[126:129], v[170:173], v[110:113]
	v_mfma_f32_16x16x32_bf16 v[98:101], v[138:141], v[170:173], v[98:101]
	v_mfma_f32_16x16x32_bf16 v[62:65], v[126:129], v[178:181], v[62:65]
	v_mfma_f32_16x16x32_bf16 v[58:61], v[138:141], v[178:181], v[58:61]
	v_mfma_f32_16x16x32_bf16 v[46:49], v[126:129], v[186:189], v[46:49]
	v_mfma_f32_16x16x32_bf16 v[42:45], v[138:141], v[186:189], v[42:45]
	v_mfma_f32_16x16x32_bf16 v[130:133], v[134:137], v[166:169], v[130:133]
	v_mfma_f32_16x16x32_bf16 v[118:121], v[142:145], v[166:169], v[118:121]
	v_mfma_f32_16x16x32_bf16 v[110:113], v[134:137], v[174:177], v[110:113]
	v_mfma_f32_16x16x32_bf16 v[98:101], v[142:145], v[174:177], v[98:101]
	v_mfma_f32_16x16x32_bf16 v[62:65], v[134:137], v[182:185], v[62:65]
	v_mfma_f32_16x16x32_bf16 v[58:61], v[142:145], v[182:185], v[58:61]
	v_mfma_f32_16x16x32_bf16 v[46:49], v[134:137], v[190:193], v[46:49]
	v_mfma_f32_16x16x32_bf16 v[42:45], v[142:145], v[190:193], v[42:45]
	v_mfma_f32_16x16x32_bf16 v[102:105], v[146:149], v[162:165], v[102:105]
	v_mfma_f32_16x16x32_bf16 v[74:77], v[154:157], v[162:165], v[74:77]
	v_mfma_f32_16x16x32_bf16 v[78:81], v[146:149], v[170:173], v[78:81]
	v_mfma_f32_16x16x32_bf16 v[90:93], v[154:157], v[170:173], v[90:93]
	v_mfma_f32_16x16x32_bf16 v[34:37], v[146:149], v[178:181], v[34:37]
	v_mfma_f32_16x16x32_bf16 v[26:29], v[154:157], v[178:181], v[26:29]
	v_mfma_f32_16x16x32_bf16 v[14:17], v[146:149], v[186:189], v[14:17]
	v_mfma_f32_16x16x32_bf16 v[2:5], v[154:157], v[186:189], v[2:5]
	v_mfma_f32_16x16x32_bf16 v[102:105], v[150:153], v[166:169], v[102:105]
	v_mfma_f32_16x16x32_bf16 v[74:77], v[158:161], v[166:169], v[74:77]
	v_mfma_f32_16x16x32_bf16 v[78:81], v[150:153], v[174:177], v[78:81]
	v_mfma_f32_16x16x32_bf16 v[90:93], v[158:161], v[174:177], v[90:93]
	v_mfma_f32_16x16x32_bf16 v[34:37], v[150:153], v[182:185], v[34:37]
	v_mfma_f32_16x16x32_bf16 v[26:29], v[158:161], v[182:185], v[26:29]
	v_mfma_f32_16x16x32_bf16 v[14:17], v[150:153], v[190:193], v[14:17]
	v_mfma_f32_16x16x32_bf16 v[2:5], v[158:161], v[190:193], v[2:5]
	s_barrier
	s_add_i32 s30, vcc_hi, s35
	v_lshl_add_u64 v[194:195], s[6:7], 0, v[238:239]
	s_mov_b32 m0, s30
	ds_read_b128 v[162:165], v252 offset:16384
	ds_read_b128 v[166:169], v252 offset:17408
	ds_read_b128 v[170:173], v252 offset:18432
	ds_read_b128 v[174:177], v252 offset:19456
	ds_read_b128 v[178:181], v252 offset:20480
	ds_read_b128 v[182:185], v252 offset:21504
	ds_read_b128 v[186:189], v252 offset:22528
	ds_read_b128 v[190:193], v252 offset:23552
	global_load_lds_dwordx4 v[194:195], off
	s_add_i32 m0, s30, 0x2000
	s_add_u32 s30, s6, 0x80000
	v_lshl_add_u64 v[196:197], s[6:7], 0, v[242:243]
	s_addc_u32 s31, s7, 0
	s_add_i32 s86, s86, s35
	global_load_lds_dwordx4 v[196:197], off
	s_mov_b32 m0, s86
	v_lshl_add_u64 v[200:201], s[40:41], 0, v[240:241]
	global_load_lds_dwordx4 v238, s[30:31]
	s_add_i32 m0, s86, 0x2000
	s_nop 0
	global_load_lds_dwordx4 v242, s[30:31]
	v_lshl_add_u64 v[198:199], s[40:41], 0, v[236:237]
	s_mov_b32 m0, s36
	s_nop 0
	global_load_lds_dwordx4 v[198:199], off
	s_mov_b32 m0, s37
	s_nop 0
	global_load_lds_dwordx4 v[200:201], off
	s_waitcnt vmcnt(8)
	s_waitcnt lgkmcnt(0)
	s_barrier
	s_waitcnt lgkmcnt(0)
	v_mfma_f32_16x16x32_bf16 v[54:57], v[126:129], v[162:165], v[54:57]
	v_mfma_f32_16x16x32_bf16 v[50:53], v[138:141], v[162:165], v[50:53]
	v_mfma_f32_16x16x32_bf16 v[38:41], v[126:129], v[170:173], v[38:41]
	v_mfma_f32_16x16x32_bf16 v[30:33], v[138:141], v[170:173], v[30:33]
	v_mfma_f32_16x16x32_bf16 v[86:89], v[126:129], v[178:181], v[86:89]
	v_mfma_f32_16x16x32_bf16 v[122:125], v[138:141], v[178:181], v[122:125]
	v_mfma_f32_16x16x32_bf16 v[114:117], v[126:129], v[186:189], v[114:117]
	v_mfma_f32_16x16x32_bf16 v[106:109], v[138:141], v[186:189], v[106:109]
	v_mfma_f32_16x16x32_bf16 v[54:57], v[134:137], v[166:169], v[54:57]
	v_mfma_f32_16x16x32_bf16 v[50:53], v[142:145], v[166:169], v[50:53]
	v_mfma_f32_16x16x32_bf16 v[38:41], v[134:137], v[174:177], v[38:41]
	v_mfma_f32_16x16x32_bf16 v[30:33], v[142:145], v[174:177], v[30:33]
	v_mfma_f32_16x16x32_bf16 v[86:89], v[134:137], v[182:185], v[86:89]
	v_mfma_f32_16x16x32_bf16 v[122:125], v[142:145], v[182:185], v[122:125]
	v_mfma_f32_16x16x32_bf16 v[114:117], v[134:137], v[190:193], v[114:117]
	v_mfma_f32_16x16x32_bf16 v[106:109], v[142:145], v[190:193], v[106:109]
	v_mfma_f32_16x16x32_bf16 v[22:25], v[146:149], v[162:165], v[22:25]
	v_mfma_f32_16x16x32_bf16 v[18:21], v[154:157], v[162:165], v[18:21]
	v_mfma_f32_16x16x32_bf16 v[10:13], v[146:149], v[170:173], v[10:13]
	v_mfma_f32_16x16x32_bf16 v[6:9], v[154:157], v[170:173], v[6:9]
	v_mfma_f32_16x16x32_bf16 v[82:85], v[146:149], v[178:181], v[82:85]
	v_mfma_f32_16x16x32_bf16 v[94:97], v[154:157], v[178:181], v[94:97]
	v_mfma_f32_16x16x32_bf16 v[70:73], v[146:149], v[186:189], v[70:73]
	v_mfma_f32_16x16x32_bf16 v[66:69], v[154:157], v[186:189], v[66:69]
	v_mfma_f32_16x16x32_bf16 v[22:25], v[150:153], v[166:169], v[22:25]
	v_mfma_f32_16x16x32_bf16 v[18:21], v[158:161], v[166:169], v[18:21]
	v_mfma_f32_16x16x32_bf16 v[10:13], v[150:153], v[174:177], v[10:13]
	v_mfma_f32_16x16x32_bf16 v[6:9], v[158:161], v[174:177], v[6:9]
	v_mfma_f32_16x16x32_bf16 v[82:85], v[150:153], v[182:185], v[82:85]
	v_mfma_f32_16x16x32_bf16 v[94:97], v[158:161], v[182:185], v[94:97]
	v_mfma_f32_16x16x32_bf16 v[70:73], v[150:153], v[190:193], v[70:73]
	v_mfma_f32_16x16x32_bf16 v[66:69], v[158:161], v[190:193], v[66:69]
	s_barrier
; #define PG8_STAGE(bufoff, gbase, voff) do { _Pragma("unroll") for (int _i = 0; _i < 2; ++_i) \
;         __builtin_amdgcn_global_load_lds((const unsigned*)((const char*)(gbase) + (voff)[_i]), (PG8_LAS unsigned*)(lds + (bufoff) + ldsw + _i * 8192), 16, 0, 0); } while (0)
; #define PG8_LDA(dst, b, h) do { _Pragma("unroll") for (int m = 0; m < 4; ++m) _Pragma("unroll") for (int k = 0; k < 2; ++k) dst[m][k] = *(const PG8_LAS bf16x8*)(lds + PG8_SA(b, h) + aoff + m * 2048 + k * 1024); } while (0)
; #define PG8_LDB(dst, b, h) do { _Pragma("unroll") for (int n = 0; n < 2; ++n) _Pragma("unroll") for (int k = 0; k < 2; ++k) dst[n][k] = *(const PG8_LAS bf16x8*)(lds + PG8_SB(b, h) + boff + n * 2048 + k * 1024); } while (0)
; #define PG8_MMA(ai, bj, At, Bt) do { __builtin_amdgcn_s_setprio(1); _Pragma("unroll") for (int m = 0; m < 4; ++m) _Pragma("unroll") for (int n = 0; n < 2; ++n) _Pragma("unroll") for (int k = 0; k < 2; ++k) \
;         acc[ai][bj][m][n] = __builtin_amdgcn_mfma_f32_16x16x32_bf16(Bt[n][k], At[m][k], acc[ai][bj][m][n], 0, 0, 0); __builtin_amdgcn_s_setprio(0); } while (0)
; #define PG8_WAIT_V(n) asm volatile("s_waitcnt vmcnt(" #n ")" ::: "memory")
; #define PG8_WAIT_L(n) asm volatile("s_waitcnt lgkmcnt(" #n ")" ::: "memory")
; #define PG8_BAR __builtin_amdgcn_s_barrier()
; #define PG8_SCHED __builtin_amdgcn_sched_barrier(0)
; template <class Epi, class Sched, bool ALIGN_EPI = false, bool SP2 = false>
; __device__ __forceinline__ void gemm_phase(PG8_LAS unsigned char* lds, const Gemm g, const Sched& S, const Epi& E, int wave_s) {
;     ...
;             PG8_LDB(B0, 1, 0); PG8_LDB(B1, 1, 1); PG8_SCHED; PG8_LDA(At, 1, 0); PG8_STAGE(PG8_SA(0, 1), a2 + hstepA, voffA);
;             PG8_WAIT_V(8); PG8_WAIT_L(0); PG8_BAR; PG8_MMA(0, 0, At, B0); PG8_MMA(0, 1, At, B1); PG8_BAR; PG8_SCHED;
;             PG8_LDA(At, 1, 1); PG8_STAGE(PG8_SB(1, 0), b3, voffB); PG8_STAGE(PG8_SB(1, 1), b3 + hstepB, voffB); PG8_STAGE(PG8_SA(1, 0), a3, voffA);
;             PG8_WAIT_V(8); PG8_WAIT_L(0); PG8_BAR; PG8_MMA(1, 0, At, B0); PG8_MMA(1, 1, At, B1); PG8_BAR; PG8_SCHED;
;     ...
;         if constexpr (ALIGN_EPI) { if (wr == 0) PG8_BAR; }
	s_add_i32 s86, 0, 0x18000
	s_add_i32 s87, 0, 0x1c000
	ds_read_b128 v[126:129], v230
	ds_read_b128 v[134:137], v230 offset:1024
	ds_read_b128 v[138:141], v230 offset:2048
	ds_read_b128 v[142:145], v230 offset:3072
	ds_read_b128 v[146:149], v231
	ds_read_b128 v[150:153], v231 offset:1024
	ds_read_b128 v[154:157], v231 offset:2048
	ds_read_b128 v[158:161], v231 offset:3072
	s_add_u32 s30, s40, 0x4000
	s_addc_u32 s31, s41, 0
	s_mov_b32 m0, s42
	ds_read_b128 v[162:165], v252 offset:32768
	ds_read_b128 v[166:169], v252 offset:33792
	ds_read_b128 v[170:173], v252 offset:34816
	ds_read_b128 v[174:177], v252 offset:35840
	ds_read_b128 v[178:181], v252 offset:36864
	ds_read_b128 v[182:185], v252 offset:37888
	ds_read_b128 v[186:189], v252 offset:38912
	ds_read_b128 v[190:193], v252 offset:39936
	global_load_lds_dwordx4 v236, s[30:31]
	v_lshl_add_u64 v[202:203], s[30:31], 0, v[240:241]
	s_mov_b32 m0, s43
	s_nop 0
	global_load_lds_dwordx4 v[202:203], off
	s_waitcnt vmcnt(8)
	s_waitcnt lgkmcnt(0)
	s_barrier
	s_waitcnt lgkmcnt(0)
	v_mfma_f32_16x16x32_bf16 v[130:133], v[126:129], v[162:165], v[130:133]
	v_mfma_f32_16x16x32_bf16 v[118:121], v[138:141], v[162:165], v[118:121]
	v_mfma_f32_16x16x32_bf16 v[110:113], v[126:129], v[170:173], v[110:113]
	v_mfma_f32_16x16x32_bf16 v[98:101], v[138:141], v[170:173], v[98:101]
	v_mfma_f32_16x16x32_bf16 v[62:65], v[126:129], v[178:181], v[62:65]
	v_mfma_f32_16x16x32_bf16 v[58:61], v[138:141], v[178:181], v[58:61]
	v_mfma_f32_16x16x32_bf16 v[46:49], v[126:129], v[186:189], v[46:49]
	v_mfma_f32_16x16x32_bf16 v[42:45], v[138:141], v[186:189], v[42:45]
	v_mfma_f32_16x16x32_bf16 v[130:133], v[134:137], v[166:169], v[130:133]
	v_mfma_f32_16x16x32_bf16 v[118:121], v[142:145], v[166:169], v[118:121]
	v_mfma_f32_16x16x32_bf16 v[110:113], v[134:137], v[174:177], v[110:113]
	v_mfma_f32_16x16x32_bf16 v[98:101], v[142:145], v[174:177], v[98:101]
	v_mfma_f32_16x16x32_bf16 v[62:65], v[134:137], v[182:185], v[62:65]
	v_mfma_f32_16x16x32_bf16 v[58:61], v[142:145], v[182:185], v[58:61]
	v_mfma_f32_16x16x32_bf16 v[46:49], v[134:137], v[190:193], v[46:49]
	v_mfma_f32_16x16x32_bf16 v[42:45], v[142:145], v[190:193], v[42:45]
	v_mfma_f32_16x16x32_bf16 v[102:105], v[146:149], v[162:165], v[102:105]
	v_mfma_f32_16x16x32_bf16 v[74:77], v[154:157], v[162:165], v[74:77]
	v_mfma_f32_16x16x32_bf16 v[78:81], v[146:149], v[170:173], v[78:81]
	v_mfma_f32_16x16x32_bf16 v[90:93], v[154:157], v[170:173], v[90:93]
	v_mfma_f32_16x16x32_bf16 v[34:37], v[146:149], v[178:181], v[34:37]
	v_mfma_f32_16x16x32_bf16 v[26:29], v[154:157], v[178:181], v[26:29]
	v_mfma_f32_16x16x32_bf16 v[14:17], v[146:149], v[186:189], v[14:17]
	v_mfma_f32_16x16x32_bf16 v[2:5], v[154:157], v[186:189], v[2:5]
	v_mfma_f32_16x16x32_bf16 v[102:105], v[150:153], v[166:169], v[102:105]
	v_mfma_f32_16x16x32_bf16 v[74:77], v[158:161], v[166:169], v[74:77]
	v_mfma_f32_16x16x32_bf16 v[78:81], v[150:153], v[174:177], v[78:81]
	v_mfma_f32_16x16x32_bf16 v[90:93], v[158:161], v[174:177], v[90:93]
	v_mfma_f32_16x16x32_bf16 v[34:37], v[150:153], v[182:185], v[34:37]
	v_mfma_f32_16x16x32_bf16 v[26:29], v[158:161], v[182:185], v[26:29]
	v_mfma_f32_16x16x32_bf16 v[14:17], v[150:153], v[190:193], v[14:17]
	v_mfma_f32_16x16x32_bf16 v[2:5], v[158:161], v[190:193], v[2:5]
	s_barrier
	s_add_i32 s30, s86, s35
	v_lshl_add_u64 v[194:195], v[194:195], 0, s[60:61]
	s_mov_b32 m0, s30
	ds_read_b128 v[162:165], v252 offset:49152
	ds_read_b128 v[166:169], v252 offset:50176
	ds_read_b128 v[170:173], v252 offset:51200
	ds_read_b128 v[174:177], v252 offset:52224
	ds_read_b128 v[178:181], v252 offset:53248
	ds_read_b128 v[182:185], v252 offset:54272
	ds_read_b128 v[186:189], v252 offset:55296
	ds_read_b128 v[190:193], v252 offset:56320
	global_load_lds_dwordx4 v[194:195], off
	s_add_i32 m0, s30, 0x2000
	s_add_u32 s6, s6, 0x80080
	v_lshl_add_u64 v[194:195], v[196:197], 0, s[60:61]
	s_addc_u32 s7, s7, 0
	s_add_i32 s30, s87, s35
	global_load_lds_dwordx4 v[194:195], off
	s_mov_b32 m0, s30
	s_nop 0
	global_load_lds_dwordx4 v238, s[6:7]
	s_add_i32 m0, s30, 0x2000
	s_nop 0
	global_load_lds_dwordx4 v242, s[6:7]
	v_lshl_add_u64 v[194:195], v[198:199], 0, s[60:61]
	s_mov_b32 m0, s77
	s_nop 0
	global_load_lds_dwordx4 v[194:195], off
	v_lshl_add_u64 v[194:195], v[200:201], 0, s[60:61]
	s_mov_b32 m0, s94
	s_nop 0
	global_load_lds_dwordx4 v[194:195], off
	s_waitcnt vmcnt(8)
	s_waitcnt lgkmcnt(0)
	s_barrier
	s_waitcnt lgkmcnt(0)
	v_mfma_f32_16x16x32_bf16 v[54:57], v[126:129], v[162:165], v[54:57]
	v_mfma_f32_16x16x32_bf16 v[50:53], v[138:141], v[162:165], v[50:53]
	v_mfma_f32_16x16x32_bf16 v[38:41], v[126:129], v[170:173], v[38:41]
	v_mfma_f32_16x16x32_bf16 v[30:33], v[138:141], v[170:173], v[30:33]
	v_mfma_f32_16x16x32_bf16 v[86:89], v[126:129], v[178:181], v[86:89]
	v_mfma_f32_16x16x32_bf16 v[122:125], v[138:141], v[178:181], v[122:125]
	v_mfma_f32_16x16x32_bf16 v[114:117], v[126:129], v[186:189], v[114:117]
	v_mfma_f32_16x16x32_bf16 v[106:109], v[138:141], v[186:189], v[106:109]
	v_mfma_f32_16x16x32_bf16 v[54:57], v[134:137], v[166:169], v[54:57]
	v_mfma_f32_16x16x32_bf16 v[50:53], v[142:145], v[166:169], v[50:53]
	v_mfma_f32_16x16x32_bf16 v[38:41], v[134:137], v[174:177], v[38:41]
	v_mfma_f32_16x16x32_bf16 v[30:33], v[142:145], v[174:177], v[30:33]
	v_mfma_f32_16x16x32_bf16 v[86:89], v[134:137], v[182:185], v[86:89]
	v_mfma_f32_16x16x32_bf16 v[122:125], v[142:145], v[182:185], v[122:125]
	v_mfma_f32_16x16x32_bf16 v[114:117], v[134:137], v[190:193], v[114:117]
	v_mfma_f32_16x16x32_bf16 v[106:109], v[142:145], v[190:193], v[106:109]
	v_mfma_f32_16x16x32_bf16 v[22:25], v[146:149], v[162:165], v[22:25]
	v_mfma_f32_16x16x32_bf16 v[18:21], v[154:157], v[162:165], v[18:21]
	v_mfma_f32_16x16x32_bf16 v[10:13], v[146:149], v[170:173], v[10:13]
	v_mfma_f32_16x16x32_bf16 v[6:9], v[154:157], v[170:173], v[6:9]
	v_mfma_f32_16x16x32_bf16 v[82:85], v[146:149], v[178:181], v[82:85]
	v_mfma_f32_16x16x32_bf16 v[94:97], v[154:157], v[178:181], v[94:97]
	v_mfma_f32_16x16x32_bf16 v[70:73], v[146:149], v[186:189], v[70:73]
	v_mfma_f32_16x16x32_bf16 v[66:69], v[154:157], v[186:189], v[66:69]
	v_mfma_f32_16x16x32_bf16 v[22:25], v[150:153], v[166:169], v[22:25]
	v_mfma_f32_16x16x32_bf16 v[18:21], v[158:161], v[166:169], v[18:21]
	v_mfma_f32_16x16x32_bf16 v[10:13], v[150:153], v[174:177], v[10:13]
	v_mfma_f32_16x16x32_bf16 v[6:9], v[158:161], v[174:177], v[6:9]
	v_mfma_f32_16x16x32_bf16 v[82:85], v[150:153], v[182:185], v[82:85]
	v_mfma_f32_16x16x32_bf16 v[94:97], v[158:161], v[182:185], v[94:97]
	v_mfma_f32_16x16x32_bf16 v[70:73], v[150:153], v[190:193], v[70:73]
	v_mfma_f32_16x16x32_bf16 v[66:69], v[158:161], v[190:193], v[66:69]
	s_barrier
	s_add_i32 vcc_lo, vcc_lo, 2
	s_add_u32 s89, s89, 0x100
	s_addc_u32 s91, s91, 0
	s_cmp_gt_u32 vcc_lo, 29
	s_mov_b64 s[30:31], s[4:5]
	s_cbranch_scc0 .LBB0_691
	s_and_b64 vcc, exec, s[26:27]
	s_cbranch_vccz .LBB0_694
	s_barrier

; #define PG8_STAGE(bufoff, gbase, voff) do { _Pragma("unroll") for (int _i = 0; _i < 2; ++_i) \
;         __builtin_amdgcn_global_load_lds((const unsigned*)((const char*)(gbase) + (voff)[_i]), (PG8_LAS unsigned*)(lds + (bufoff) + ldsw + _i * 8192), 16, 0, 0); } while (0)
; #define PG8_LDA(dst, b, h) do { _Pragma("unroll") for (int m = 0; m < 4; ++m) _Pragma("unroll") for (int k = 0; k < 2; ++k) dst[m][k] = *(const PG8_LAS bf16x8*)(lds + PG8_SA(b, h) + aoff + m * 2048 + k * 1024); } while (0)
; #define PG8_LDB(dst, b, h) do { _Pragma("unroll") for (int n = 0; n < 2; ++n) _Pragma("unroll") for (int k = 0; k < 2; ++k) dst[n][k] = *(const PG8_LAS bf16x8*)(lds + PG8_SB(b, h) + boff + n * 2048 + k * 1024); } while (0)
; #define PG8_WAIT_V(n) asm volatile("s_waitcnt vmcnt(" #n ")" ::: "memory")
; #define PG8_WAIT_L(n) asm volatile("s_waitcnt lgkmcnt(" #n ")" ::: "memory")
; #define PG8_BAR __builtin_amdgcn_s_barrier()
; template <class Epi, class Sched, bool ALIGN_EPI = false, bool SP2 = false>
; __device__ __forceinline__ void gemm_phase(PG8_LAS unsigned char* lds, const Gemm g, const Sched& S, const Epi& E, int wave_s) {
;     ...
;         const bool has_next = S.next(ui + 1, nxt);
;         const char* nA = has_next ? (const char*)g.A + (size_t)nxt.pm * tstepA + (size_t)(nxt.pn / g.npg) * (size_t)(K * 2) : cA; const char* nB = has_next ? (const char*)g.Bt + (size_t)nxt.pn * tstepB : cB;
;         for (int t = 0; t < nt; t += 2) {
;             const bool last = (t == nt - 2);
;             const char* a1 = cA + (size_t)(t + 1) * kstep;
;             const char* a2 = last ? nA : cA + (size_t)(t + 2) * kstep; const char* b2 = last ? nB : cB + (size_t)(t + 2) * kstep;
;             const char* a3 = a2 + kstep; const char* b3 = b2 + kstep;
;             if (last && has_next) S.a_ready(nxt);
;             if constexpr (SP2) {
;             PG8_LDB(B0, 0, 0); PG8_LDB(B1, 0, 1); PG8_SCHED; PG8_LDA(At, 0, 0); PG8_STAGE(PG8_SA(1, 1), a1 + hstepA, voffA);
;             PG8_WAIT_V(8); PG8_WAIT_L(0); PG8_BAR; PG8_MMA(0, 0, At, B0); PG8_MMA(0, 1, At, B1); PG8_BAR; PG8_SCHED;
;             PG8_LDA(At, 0, 1); PG8_STAGE(PG8_SB(0, 0), b2, voffB); PG8_STAGE(PG8_SB(0, 1), b2 + hstepB, voffB); PG8_STAGE(PG8_SA(0, 0), a2, voffA);
;             PG8_WAIT_V(8); PG8_WAIT_L(0); PG8_BAR; PG8_MMA(1, 0, At, B0); PG8_MMA(1, 1, At, B1); PG8_BAR; PG8_SCHED;
.LBB0_785:
	v_add_u32_e32 v228, 0x10000, v211
	v_add_u32_e32 v229, 0x14000, v211
	v_add_u32_e32 v230, 0x18000, v211
	v_add_u32_e32 v231, 0x1c000, v211
	s_add_u32 s2, s30, 0x100
	s_addc_u32 s3, s31, 0
	s_mov_b32 s81, -2
	s_add_u32 s4, s8, 0x100
	s_addc_u32 s5, s9, 0
	s_add_i32 s84, 0, 0x10000
	s_cmpk_eq_i32 s81, 0x54
	s_cselect_b32 s31, s95, s5
	s_cselect_b32 s30, s94, s4
	s_cselect_b32 s7, s97, s3
	s_cselect_b32 s6, s96, s2
	s_add_i32 s85, 0, 0x14000
	ds_read_b128 v[78:81], v228
	ds_read_b128 v[86:89], v228 offset:1024
	ds_read_b128 v[102:105], v228 offset:2048
	ds_read_b128 v[110:113], v228 offset:3072
	ds_read_b128 v[122:125], v229
	ds_read_b128 v[134:137], v229 offset:1024
	ds_read_b128 v[146:149], v229 offset:2048
	ds_read_b128 v[150:153], v229 offset:3072
	s_add_i32 m0, s35, 0xc000
	ds_read_b128 v[162:165], v212
	ds_read_b128 v[166:169], v212 offset:1024
	ds_read_b128 v[170:173], v212 offset:2048
	ds_read_b128 v[174:177], v212 offset:3072
	ds_read_b128 v[178:181], v212 offset:4096
	ds_read_b128 v[182:185], v212 offset:5120
	ds_read_b128 v[186:189], v212 offset:6144
	ds_read_b128 v[202:205], v212 offset:7168
	global_load_lds_dwordx4 v198, s[8:9]
	s_add_i32 m0, s35, 0xe000
	s_nop 0
	global_load_lds_dwordx4 v200, s[8:9]
	s_waitcnt vmcnt(8)
	s_waitcnt lgkmcnt(0)
	s_barrier
	s_waitcnt lgkmcnt(0)
	v_mfma_f32_16x16x32_bf16 v[158:161], v[78:81], v[162:165], 0
	v_mfma_f32_16x16x32_bf16 v[154:157], v[102:105], v[162:165], 0
	v_mfma_f32_16x16x32_bf16 v[130:133], v[78:81], v[170:173], 0
	v_mfma_f32_16x16x32_bf16 v[126:129], v[102:105], v[170:173], 0
	v_mfma_f32_16x16x32_bf16 v[106:109], v[78:81], v[178:181], 0
	v_mfma_f32_16x16x32_bf16 v[98:101], v[102:105], v[178:181], 0
	v_mfma_f32_16x16x32_bf16 v[82:85], v[78:81], v[186:189], 0
	v_mfma_f32_16x16x32_bf16 v[74:77], v[102:105], v[186:189], 0
	v_mfma_f32_16x16x32_bf16 v[158:161], v[86:89], v[166:169], v[158:161]
	v_mfma_f32_16x16x32_bf16 v[154:157], v[110:113], v[166:169], v[154:157]
	v_mfma_f32_16x16x32_bf16 v[130:133], v[86:89], v[174:177], v[130:133]
	v_mfma_f32_16x16x32_bf16 v[126:129], v[110:113], v[174:177], v[126:129]
	v_mfma_f32_16x16x32_bf16 v[106:109], v[86:89], v[182:185], v[106:109]
	v_mfma_f32_16x16x32_bf16 v[98:101], v[110:113], v[182:185], v[98:101]
	v_mfma_f32_16x16x32_bf16 v[82:85], v[86:89], v[202:205], v[82:85]
	v_mfma_f32_16x16x32_bf16 v[74:77], v[110:113], v[202:205], v[74:77]
	v_mfma_f32_16x16x32_bf16 v[142:145], v[122:125], v[162:165], 0
	v_mfma_f32_16x16x32_bf16 v[138:141], v[146:149], v[162:165], 0
	v_mfma_f32_16x16x32_bf16 v[118:121], v[122:125], v[170:173], 0
	v_mfma_f32_16x16x32_bf16 v[114:117], v[146:149], v[170:173], 0
	v_mfma_f32_16x16x32_bf16 v[94:97], v[122:125], v[178:181], 0
	v_mfma_f32_16x16x32_bf16 v[90:93], v[146:149], v[178:181], 0
	v_mfma_f32_16x16x32_bf16 v[70:73], v[122:125], v[186:189], 0
	v_mfma_f32_16x16x32_bf16 v[66:69], v[146:149], v[186:189], 0
	v_mfma_f32_16x16x32_bf16 v[142:145], v[134:137], v[166:169], v[142:145]
	v_mfma_f32_16x16x32_bf16 v[138:141], v[150:153], v[166:169], v[138:141]
	v_mfma_f32_16x16x32_bf16 v[118:121], v[134:137], v[174:177], v[118:121]
	v_mfma_f32_16x16x32_bf16 v[114:117], v[150:153], v[174:177], v[114:117]
	v_mfma_f32_16x16x32_bf16 v[94:97], v[134:137], v[182:185], v[94:97]
	v_mfma_f32_16x16x32_bf16 v[90:93], v[150:153], v[182:185], v[90:93]
	v_mfma_f32_16x16x32_bf16 v[70:73], v[134:137], v[202:205], v[70:73]
	v_mfma_f32_16x16x32_bf16 v[66:69], v[150:153], v[202:205], v[66:69]
	s_barrier
	s_add_i32 s8, s84, s22
	v_lshl_add_u64 v[206:207], s[6:7], 0, v[194:195]
	s_mov_b32 m0, s8
	ds_read_b128 v[162:165], v212 offset:16384
	ds_read_b128 v[166:169], v212 offset:17408
	ds_read_b128 v[170:173], v212 offset:18432
	ds_read_b128 v[174:177], v212 offset:19456
	ds_read_b128 v[178:181], v212 offset:20480
	ds_read_b128 v[182:185], v212 offset:21504
	ds_read_b128 v[186:189], v212 offset:22528
	ds_read_b128 v[202:205], v212 offset:23552
	global_load_lds_dwordx4 v[206:207], off
	s_add_i32 m0, s8, 0x2000
	s_add_u32 s8, s6, 0x160000
	v_lshl_add_u64 v[208:209], s[6:7], 0, v[190:191]
	s_addc_u32 s9, s7, 0
	s_add_i32 s84, s85, s22
	global_load_lds_dwordx4 v[208:209], off
	s_mov_b32 m0, s84
	v_lshl_add_u64 v[216:217], s[30:31], 0, v[192:193]
	global_load_lds_dwordx4 v194, s[8:9]
	s_add_i32 m0, s84, 0x2000
	s_nop 0
	global_load_lds_dwordx4 v190, s[8:9]
	v_lshl_add_u64 v[214:215], s[30:31], 0, v[196:197]
	s_mov_b32 m0, s35
	s_nop 0
	global_load_lds_dwordx4 v[214:215], off
	s_mov_b32 m0, s36
	s_nop 0
	global_load_lds_dwordx4 v[216:217], off
	s_waitcnt vmcnt(8)
	s_waitcnt lgkmcnt(0)
	s_barrier
	s_waitcnt lgkmcnt(0)
	v_mfma_f32_16x16x32_bf16 v[62:65], v[78:81], v[162:165], 0
	v_mfma_f32_16x16x32_bf16 v[58:61], v[102:105], v[162:165], 0
	v_mfma_f32_16x16x32_bf16 v[46:49], v[78:81], v[170:173], 0
	v_mfma_f32_16x16x32_bf16 v[42:45], v[102:105], v[170:173], 0
	v_mfma_f32_16x16x32_bf16 v[30:33], v[78:81], v[178:181], 0
	v_mfma_f32_16x16x32_bf16 v[26:29], v[102:105], v[178:181], 0
	v_mfma_f32_16x16x32_bf16 v[14:17], v[78:81], v[186:189], 0
	v_mfma_f32_16x16x32_bf16 v[10:13], v[102:105], v[186:189], 0
	v_mfma_f32_16x16x32_bf16 v[62:65], v[86:89], v[166:169], v[62:65]
	v_mfma_f32_16x16x32_bf16 v[58:61], v[110:113], v[166:169], v[58:61]
	v_mfma_f32_16x16x32_bf16 v[46:49], v[86:89], v[174:177], v[46:49]
	v_mfma_f32_16x16x32_bf16 v[42:45], v[110:113], v[174:177], v[42:45]
	v_mfma_f32_16x16x32_bf16 v[30:33], v[86:89], v[182:185], v[30:33]
	v_mfma_f32_16x16x32_bf16 v[26:29], v[110:113], v[182:185], v[26:29]
	v_mfma_f32_16x16x32_bf16 v[14:17], v[86:89], v[202:205], v[14:17]
	v_mfma_f32_16x16x32_bf16 v[10:13], v[110:113], v[202:205], v[10:13]
	v_mfma_f32_16x16x32_bf16 v[54:57], v[122:125], v[162:165], 0
	v_mfma_f32_16x16x32_bf16 v[50:53], v[146:149], v[162:165], 0
	v_mfma_f32_16x16x32_bf16 v[38:41], v[122:125], v[170:173], 0
	v_mfma_f32_16x16x32_bf16 v[34:37], v[146:149], v[170:173], 0
	v_mfma_f32_16x16x32_bf16 v[22:25], v[122:125], v[178:181], 0
	v_mfma_f32_16x16x32_bf16 v[18:21], v[146:149], v[178:181], 0
	v_mfma_f32_16x16x32_bf16 v[6:9], v[122:125], v[186:189], 0
	v_mfma_f32_16x16x32_bf16 v[2:5], v[146:149], v[186:189], 0
	v_mfma_f32_16x16x32_bf16 v[54:57], v[134:137], v[166:169], v[54:57]
	v_mfma_f32_16x16x32_bf16 v[50:53], v[150:153], v[166:169], v[50:53]
	v_mfma_f32_16x16x32_bf16 v[38:41], v[134:137], v[174:177], v[38:41]
	v_mfma_f32_16x16x32_bf16 v[34:37], v[150:153], v[174:177], v[34:37]
	v_mfma_f32_16x16x32_bf16 v[22:25], v[134:137], v[182:185], v[22:25]
	v_mfma_f32_16x16x32_bf16 v[18:21], v[150:153], v[182:185], v[18:21]
	v_mfma_f32_16x16x32_bf16 v[6:9], v[134:137], v[202:205], v[6:9]
	v_mfma_f32_16x16x32_bf16 v[2:5], v[150:153], v[202:205], v[2:5]
	s_barrier
; #define PG8_STAGE(bufoff, gbase, voff) do { _Pragma("unroll") for (int _i = 0; _i < 2; ++_i) \
;         __builtin_amdgcn_global_load_lds((const unsigned*)((const char*)(gbase) + (voff)[_i]), (PG8_LAS unsigned*)(lds + (bufoff) + ldsw + _i * 8192), 16, 0, 0); } while (0)
; #define PG8_LDA(dst, b, h) do { _Pragma("unroll") for (int m = 0; m < 4; ++m) _Pragma("unroll") for (int k = 0; k < 2; ++k) dst[m][k] = *(const PG8_LAS bf16x8*)(lds + PG8_SA(b, h) + aoff + m * 2048 + k * 1024); } while (0)
; #define PG8_LDB(dst, b, h) do { _Pragma("unroll") for (int n = 0; n < 2; ++n) _Pragma("unroll") for (int k = 0; k < 2; ++k) dst[n][k] = *(const PG8_LAS bf16x8*)(lds + PG8_SB(b, h) + boff + n * 2048 + k * 1024); } while (0)
; #define PG8_MMA(ai, bj, At, Bt) do { __builtin_amdgcn_s_setprio(1); _Pragma("unroll") for (int m = 0; m < 4; ++m) _Pragma("unroll") for (int n = 0; n < 2; ++n) _Pragma("unroll") for (int k = 0; k < 2; ++k) \
;         acc[ai][bj][m][n] = __builtin_amdgcn_mfma_f32_16x16x32_bf16(Bt[n][k], At[m][k], acc[ai][bj][m][n], 0, 0, 0); __builtin_amdgcn_s_setprio(0); } while (0)
; #define PG8_WAIT_V(n) asm volatile("s_waitcnt vmcnt(" #n ")" ::: "memory")
; #define PG8_WAIT_L(n) asm volatile("s_waitcnt lgkmcnt(" #n ")" ::: "memory")
; #define PG8_BAR __builtin_amdgcn_s_barrier()
; #define PG8_SCHED __builtin_amdgcn_sched_barrier(0)
; template <class Epi, class Sched, bool ALIGN_EPI = false, bool SP2 = false>
; __device__ __forceinline__ void gemm_phase(PG8_LAS unsigned char* lds, const Gemm g, const Sched& S, const Epi& E, int wave_s) {
;     ...
;             PG8_LDB(B0, 1, 0); PG8_LDB(B1, 1, 1); PG8_SCHED; PG8_LDA(At, 1, 0); PG8_STAGE(PG8_SA(0, 1), a2 + hstepA, voffA);
;             PG8_WAIT_V(8); PG8_WAIT_L(0); PG8_BAR; PG8_MMA(0, 0, At, B0); PG8_MMA(0, 1, At, B1); PG8_BAR; PG8_SCHED;
;             PG8_LDA(At, 1, 1); PG8_STAGE(PG8_SB(1, 0), b3, voffB); PG8_STAGE(PG8_SB(1, 1), b3 + hstepB, voffB); PG8_STAGE(PG8_SA(1, 0), a3, voffA);
;             PG8_WAIT_V(8); PG8_WAIT_L(0); PG8_BAR; PG8_MMA(1, 0, At, B0); PG8_MMA(1, 1, At, B1); PG8_BAR; PG8_SCHED;
	s_add_i32 s84, 0, 0x18000
	s_add_i32 s85, 0, 0x1c000
	ds_read_b128 v[78:81], v230
	ds_read_b128 v[86:89], v230 offset:1024
	ds_read_b128 v[102:105], v230 offset:2048
	ds_read_b128 v[110:113], v230 offset:3072
	ds_read_b128 v[122:125], v231
	ds_read_b128 v[134:137], v231 offset:1024
	ds_read_b128 v[146:149], v231 offset:2048
	ds_read_b128 v[150:153], v231 offset:3072
	s_add_u32 s8, s30, 0x160000
	s_addc_u32 s9, s31, 0
	s_mov_b32 m0, s37
	ds_read_b128 v[162:165], v212 offset:32768
	ds_read_b128 v[166:169], v212 offset:33792
	ds_read_b128 v[170:173], v212 offset:34816
	ds_read_b128 v[174:177], v212 offset:35840
	ds_read_b128 v[178:181], v212 offset:36864
	ds_read_b128 v[182:185], v212 offset:37888
	ds_read_b128 v[186:189], v212 offset:38912
	ds_read_b128 v[202:205], v212 offset:39936
	global_load_lds_dwordx4 v196, s[8:9]
	s_mov_b32 m0, s40
	s_nop 0
	global_load_lds_dwordx4 v192, s[8:9]
	s_waitcnt vmcnt(8)
	s_waitcnt lgkmcnt(0)
	s_barrier
	s_waitcnt lgkmcnt(0)
	v_mfma_f32_16x16x32_bf16 v[158:161], v[78:81], v[162:165], v[158:161]
	v_mfma_f32_16x16x32_bf16 v[154:157], v[102:105], v[162:165], v[154:157]
	v_mfma_f32_16x16x32_bf16 v[130:133], v[78:81], v[170:173], v[130:133]
	v_mfma_f32_16x16x32_bf16 v[126:129], v[102:105], v[170:173], v[126:129]
	v_mfma_f32_16x16x32_bf16 v[106:109], v[78:81], v[178:181], v[106:109]
	v_mfma_f32_16x16x32_bf16 v[98:101], v[102:105], v[178:181], v[98:101]
	v_mfma_f32_16x16x32_bf16 v[82:85], v[78:81], v[186:189], v[82:85]
	v_mfma_f32_16x16x32_bf16 v[74:77], v[102:105], v[186:189], v[74:77]
	v_mfma_f32_16x16x32_bf16 v[158:161], v[86:89], v[166:169], v[158:161]
	v_mfma_f32_16x16x32_bf16 v[154:157], v[110:113], v[166:169], v[154:157]
	v_mfma_f32_16x16x32_bf16 v[130:133], v[86:89], v[174:177], v[130:133]
	v_mfma_f32_16x16x32_bf16 v[126:129], v[110:113], v[174:177], v[126:129]
	v_mfma_f32_16x16x32_bf16 v[106:109], v[86:89], v[182:185], v[106:109]
	v_mfma_f32_16x16x32_bf16 v[98:101], v[110:113], v[182:185], v[98:101]
	v_mfma_f32_16x16x32_bf16 v[82:85], v[86:89], v[202:205], v[82:85]
	v_mfma_f32_16x16x32_bf16 v[74:77], v[110:113], v[202:205], v[74:77]
	v_mfma_f32_16x16x32_bf16 v[142:145], v[122:125], v[162:165], v[142:145]
	v_mfma_f32_16x16x32_bf16 v[138:141], v[146:149], v[162:165], v[138:141]
	v_mfma_f32_16x16x32_bf16 v[118:121], v[122:125], v[170:173], v[118:121]
	v_mfma_f32_16x16x32_bf16 v[114:117], v[146:149], v[170:173], v[114:117]
	v_mfma_f32_16x16x32_bf16 v[94:97], v[122:125], v[178:181], v[94:97]
	v_mfma_f32_16x16x32_bf16 v[90:93], v[146:149], v[178:181], v[90:93]
	v_mfma_f32_16x16x32_bf16 v[70:73], v[122:125], v[186:189], v[70:73]
	v_mfma_f32_16x16x32_bf16 v[66:69], v[146:149], v[186:189], v[66:69]
	v_mfma_f32_16x16x32_bf16 v[142:145], v[134:137], v[166:169], v[142:145]
	v_mfma_f32_16x16x32_bf16 v[138:141], v[150:153], v[166:169], v[138:141]
	v_mfma_f32_16x16x32_bf16 v[118:121], v[134:137], v[174:177], v[118:121]
	v_mfma_f32_16x16x32_bf16 v[114:117], v[150:153], v[174:177], v[114:117]
	v_mfma_f32_16x16x32_bf16 v[94:97], v[134:137], v[182:185], v[94:97]
	v_mfma_f32_16x16x32_bf16 v[90:93], v[150:153], v[182:185], v[90:93]
	v_mfma_f32_16x16x32_bf16 v[70:73], v[134:137], v[202:205], v[70:73]
	v_mfma_f32_16x16x32_bf16 v[66:69], v[150:153], v[202:205], v[66:69]
	s_barrier
	s_add_i32 s8, s84, s22
	v_lshl_add_u64 v[206:207], v[206:207], 0, s[60:61]
	s_mov_b32 m0, s8
	ds_read_b128 v[162:165], v212 offset:49152
	ds_read_b128 v[166:169], v212 offset:50176
	ds_read_b128 v[170:173], v212 offset:51200
	ds_read_b128 v[174:177], v212 offset:52224
	ds_read_b128 v[178:181], v212 offset:53248
	ds_read_b128 v[182:185], v212 offset:54272
	ds_read_b128 v[186:189], v212 offset:55296
	ds_read_b128 v[202:205], v212 offset:56320
	global_load_lds_dwordx4 v[206:207], off
	s_add_i32 m0, s8, 0x2000
	s_add_u32 s6, s6, 0x160080
	v_lshl_add_u64 v[206:207], v[208:209], 0, s[60:61]
	s_addc_u32 s7, s7, 0
	s_add_i32 s8, s85, s22
	global_load_lds_dwordx4 v[206:207], off
	s_mov_b32 m0, s8
	s_nop 0
	global_load_lds_dwordx4 v194, s[6:7]
	s_add_i32 m0, s8, 0x2000
	s_nop 0
	global_load_lds_dwordx4 v190, s[6:7]
	v_lshl_add_u64 v[206:207], v[214:215], 0, s[60:61]
	s_mov_b32 m0, s44
	s_nop 0
	global_load_lds_dwordx4 v[206:207], off
	v_lshl_add_u64 v[206:207], v[216:217], 0, s[60:61]
	s_mov_b32 m0, s45
	s_nop 0
	global_load_lds_dwordx4 v[206:207], off
	s_waitcnt vmcnt(8)
	s_waitcnt lgkmcnt(0)
	s_barrier
	s_waitcnt lgkmcnt(0)
	v_mfma_f32_16x16x32_bf16 v[62:65], v[78:81], v[162:165], v[62:65]
	v_mfma_f32_16x16x32_bf16 v[58:61], v[102:105], v[162:165], v[58:61]
	v_mfma_f32_16x16x32_bf16 v[46:49], v[78:81], v[170:173], v[46:49]
	v_mfma_f32_16x16x32_bf16 v[42:45], v[102:105], v[170:173], v[42:45]
	v_mfma_f32_16x16x32_bf16 v[30:33], v[78:81], v[178:181], v[30:33]
	v_mfma_f32_16x16x32_bf16 v[26:29], v[102:105], v[178:181], v[26:29]
	v_mfma_f32_16x16x32_bf16 v[14:17], v[78:81], v[186:189], v[14:17]
	v_mfma_f32_16x16x32_bf16 v[10:13], v[102:105], v[186:189], v[10:13]
	v_mfma_f32_16x16x32_bf16 v[62:65], v[86:89], v[166:169], v[62:65]
	v_mfma_f32_16x16x32_bf16 v[58:61], v[110:113], v[166:169], v[58:61]
	v_mfma_f32_16x16x32_bf16 v[46:49], v[86:89], v[174:177], v[46:49]
	v_mfma_f32_16x16x32_bf16 v[42:45], v[110:113], v[174:177], v[42:45]
	v_mfma_f32_16x16x32_bf16 v[30:33], v[86:89], v[182:185], v[30:33]
	v_mfma_f32_16x16x32_bf16 v[26:29], v[110:113], v[182:185], v[26:29]
	v_mfma_f32_16x16x32_bf16 v[14:17], v[86:89], v[202:205], v[14:17]
	v_mfma_f32_16x16x32_bf16 v[10:13], v[110:113], v[202:205], v[10:13]
	v_mfma_f32_16x16x32_bf16 v[54:57], v[122:125], v[162:165], v[54:57]
	v_mfma_f32_16x16x32_bf16 v[50:53], v[146:149], v[162:165], v[50:53]
	v_mfma_f32_16x16x32_bf16 v[38:41], v[122:125], v[170:173], v[38:41]
	v_mfma_f32_16x16x32_bf16 v[34:37], v[146:149], v[170:173], v[34:37]
	v_mfma_f32_16x16x32_bf16 v[22:25], v[122:125], v[178:181], v[22:25]
	v_mfma_f32_16x16x32_bf16 v[18:21], v[146:149], v[178:181], v[18:21]
	v_mfma_f32_16x16x32_bf16 v[6:9], v[122:125], v[186:189], v[6:9]
	v_mfma_f32_16x16x32_bf16 v[2:5], v[146:149], v[186:189], v[2:5]
	v_mfma_f32_16x16x32_bf16 v[54:57], v[134:137], v[166:169], v[54:57]
	v_mfma_f32_16x16x32_bf16 v[50:53], v[150:153], v[166:169], v[50:53]
	v_mfma_f32_16x16x32_bf16 v[38:41], v[134:137], v[174:177], v[38:41]
	v_mfma_f32_16x16x32_bf16 v[34:37], v[150:153], v[174:177], v[34:37]
	v_mfma_f32_16x16x32_bf16 v[22:25], v[134:137], v[182:185], v[22:25]
	v_mfma_f32_16x16x32_bf16 v[18:21], v[150:153], v[182:185], v[18:21]
	v_mfma_f32_16x16x32_bf16 v[6:9], v[134:137], v[202:205], v[6:9]
	v_mfma_f32_16x16x32_bf16 v[2:5], v[150:153], v[202:205], v[2:5]
	s_barrier
	s_add_i32 s81, s81, 2
	s_add_u32 s2, s2, 0x100
	s_addc_u32 s3, s3, 0
	s_cmpk_gt_u32 s81, 0x55
	s_mov_b64 s[8:9], s[4:5]
; #define PG8_STAGE(bufoff, gbase, voff) do { _Pragma("unroll") for (int _i = 0; _i < 2; ++_i) \
;         __builtin_amdgcn_global_load_lds((const unsigned*)((const char*)(gbase) + (voff)[_i]), (PG8_LAS unsigned*)(lds + (bufoff) + ldsw + _i * 8192), 16, 0, 0); } while (0)
; #define PG8_LDA(dst, b, h) do { _Pragma("unroll") for (int m = 0; m < 4; ++m) _Pragma("unroll") for (int k = 0; k < 2; ++k) dst[m][k] = *(const PG8_LAS bf16x8*)(lds + PG8_SA(b, h) + aoff + m * 2048 + k * 1024); } while (0)
; #define PG8_LDB(dst, b, h) do { _Pragma("unroll") for (int n = 0; n < 2; ++n) _Pragma("unroll") for (int k = 0; k < 2; ++k) dst[n][k] = *(const PG8_LAS bf16x8*)(lds + PG8_SB(b, h) + boff + n * 2048 + k * 1024); } while (0)
; #define PG8_MMA(ai, bj, At, Bt) do { __builtin_amdgcn_s_setprio(1); _Pragma("unroll") for (int m = 0; m < 4; ++m) _Pragma("unroll") for (int n = 0; n < 2; ++n) _Pragma("unroll") for (int k = 0; k < 2; ++k) \
;         acc[ai][bj][m][n] = __builtin_amdgcn_mfma_f32_16x16x32_bf16(Bt[n][k], At[m][k], acc[ai][bj][m][n], 0, 0, 0); __builtin_amdgcn_s_setprio(0); } while (0)
; #define PG8_WAIT_V(n) asm volatile("s_waitcnt vmcnt(" #n ")" ::: "memory")
; #define PG8_WAIT_L(n) asm volatile("s_waitcnt lgkmcnt(" #n ")" ::: "memory")
; #define PG8_BAR __builtin_amdgcn_s_barrier()
; #define PG8_SCHED __builtin_amdgcn_sched_barrier(0)
; template <class Epi, class Sched, bool ALIGN_EPI = false, bool SP2 = false>
; __device__ __forceinline__ void gemm_phase(PG8_LAS unsigned char* lds, const Gemm g, const Sched& S, const Epi& E, int wave_s) {
;     ...
;             PG8_LDB(B0, 0, 0); PG8_LDB(B1, 0, 1); PG8_SCHED; PG8_LDA(At, 0, 0); PG8_STAGE(PG8_SA(1, 1), a1 + hstepA, voffA);
;             PG8_WAIT_V(8); PG8_WAIT_L(0); PG8_BAR; PG8_MMA(0, 0, At, B0); PG8_MMA(0, 1, At, B1); PG8_BAR; PG8_SCHED;
;             PG8_LDA(At, 0, 1); PG8_STAGE(PG8_SB(0, 0), b2, voffB); PG8_STAGE(PG8_SB(0, 1), b2 + hstepB, voffB); PG8_STAGE(PG8_SA(0, 0), a2, voffA);
;             PG8_WAIT_V(8); PG8_WAIT_L(0); PG8_BAR; PG8_MMA(1, 0, At, B0); PG8_MMA(1, 1, At, B1); PG8_BAR; PG8_SCHED;
.LBB0_786:
	s_add_u32 s4, s8, 0x100
	s_addc_u32 s5, s9, 0
	s_add_i32 s84, 0, 0x10000
	s_cmpk_eq_i32 s81, 0x54
	s_cselect_b32 s31, s95, s5
	s_cselect_b32 s30, s94, s4
	s_cselect_b32 s7, s97, s3
	s_cselect_b32 s6, s96, s2
	s_add_i32 s85, 0, 0x14000
	ds_read_b128 v[78:81], v228
	ds_read_b128 v[86:89], v228 offset:1024
	ds_read_b128 v[102:105], v228 offset:2048
	ds_read_b128 v[110:113], v228 offset:3072
	ds_read_b128 v[122:125], v229
	ds_read_b128 v[134:137], v229 offset:1024
	ds_read_b128 v[146:149], v229 offset:2048
	ds_read_b128 v[150:153], v229 offset:3072
	s_add_i32 m0, s35, 0xc000
	ds_read_b128 v[162:165], v212
	ds_read_b128 v[166:169], v212 offset:1024
	ds_read_b128 v[170:173], v212 offset:2048
	ds_read_b128 v[174:177], v212 offset:3072
	ds_read_b128 v[178:181], v212 offset:4096
	ds_read_b128 v[182:185], v212 offset:5120
	ds_read_b128 v[186:189], v212 offset:6144
	ds_read_b128 v[202:205], v212 offset:7168
	global_load_lds_dwordx4 v198, s[8:9]
	s_add_i32 m0, s35, 0xe000
	s_nop 0
	global_load_lds_dwordx4 v200, s[8:9]
	s_waitcnt vmcnt(8)
	s_waitcnt lgkmcnt(0)
	s_barrier
	s_waitcnt lgkmcnt(0)
	v_mfma_f32_16x16x32_bf16 v[158:161], v[78:81], v[162:165], v[158:161]
	v_mfma_f32_16x16x32_bf16 v[154:157], v[102:105], v[162:165], v[154:157]
	v_mfma_f32_16x16x32_bf16 v[130:133], v[78:81], v[170:173], v[130:133]
	v_mfma_f32_16x16x32_bf16 v[126:129], v[102:105], v[170:173], v[126:129]
	v_mfma_f32_16x16x32_bf16 v[106:109], v[78:81], v[178:181], v[106:109]
	v_mfma_f32_16x16x32_bf16 v[98:101], v[102:105], v[178:181], v[98:101]
	v_mfma_f32_16x16x32_bf16 v[82:85], v[78:81], v[186:189], v[82:85]
	v_mfma_f32_16x16x32_bf16 v[74:77], v[102:105], v[186:189], v[74:77]
	v_mfma_f32_16x16x32_bf16 v[158:161], v[86:89], v[166:169], v[158:161]
	v_mfma_f32_16x16x32_bf16 v[154:157], v[110:113], v[166:169], v[154:157]
	v_mfma_f32_16x16x32_bf16 v[130:133], v[86:89], v[174:177], v[130:133]
	v_mfma_f32_16x16x32_bf16 v[126:129], v[110:113], v[174:177], v[126:129]
	v_mfma_f32_16x16x32_bf16 v[106:109], v[86:89], v[182:185], v[106:109]
	v_mfma_f32_16x16x32_bf16 v[98:101], v[110:113], v[182:185], v[98:101]
	v_mfma_f32_16x16x32_bf16 v[82:85], v[86:89], v[202:205], v[82:85]
	v_mfma_f32_16x16x32_bf16 v[74:77], v[110:113], v[202:205], v[74:77]
	v_mfma_f32_16x16x32_bf16 v[142:145], v[122:125], v[162:165], v[142:145]
	v_mfma_f32_16x16x32_bf16 v[138:141], v[146:149], v[162:165], v[138:141]
	v_mfma_f32_16x16x32_bf16 v[118:121], v[122:125], v[170:173], v[118:121]
	v_mfma_f32_16x16x32_bf16 v[114:117], v[146:149], v[170:173], v[114:117]
	v_mfma_f32_16x16x32_bf16 v[94:97], v[122:125], v[178:181], v[94:97]
	v_mfma_f32_16x16x32_bf16 v[90:93], v[146:149], v[178:181], v[90:93]
	v_mfma_f32_16x16x32_bf16 v[70:73], v[122:125], v[186:189], v[70:73]
	v_mfma_f32_16x16x32_bf16 v[66:69], v[146:149], v[186:189], v[66:69]
	v_mfma_f32_16x16x32_bf16 v[142:145], v[134:137], v[166:169], v[142:145]
	v_mfma_f32_16x16x32_bf16 v[138:141], v[150:153], v[166:169], v[138:141]
	v_mfma_f32_16x16x32_bf16 v[118:121], v[134:137], v[174:177], v[118:121]
	v_mfma_f32_16x16x32_bf16 v[114:117], v[150:153], v[174:177], v[114:117]
	v_mfma_f32_16x16x32_bf16 v[94:97], v[134:137], v[182:185], v[94:97]
	v_mfma_f32_16x16x32_bf16 v[90:93], v[150:153], v[182:185], v[90:93]
	v_mfma_f32_16x16x32_bf16 v[70:73], v[134:137], v[202:205], v[70:73]
	v_mfma_f32_16x16x32_bf16 v[66:69], v[150:153], v[202:205], v[66:69]
	s_barrier
	s_add_i32 s8, s84, s22
	v_lshl_add_u64 v[206:207], s[6:7], 0, v[194:195]
	s_mov_b32 m0, s8
	ds_read_b128 v[162:165], v212 offset:16384
	ds_read_b128 v[166:169], v212 offset:17408
	ds_read_b128 v[170:173], v212 offset:18432
	ds_read_b128 v[174:177], v212 offset:19456
	ds_read_b128 v[178:181], v212 offset:20480
	ds_read_b128 v[182:185], v212 offset:21504
	ds_read_b128 v[186:189], v212 offset:22528
	ds_read_b128 v[202:205], v212 offset:23552
	global_load_lds_dwordx4 v[206:207], off
	s_add_i32 m0, s8, 0x2000
	s_add_u32 s8, s6, 0x160000
	v_lshl_add_u64 v[208:209], s[6:7], 0, v[190:191]
	s_addc_u32 s9, s7, 0
	s_add_i32 s84, s85, s22
	global_load_lds_dwordx4 v[208:209], off
	s_mov_b32 m0, s84
	v_lshl_add_u64 v[216:217], s[30:31], 0, v[192:193]
	global_load_lds_dwordx4 v194, s[8:9]
	s_add_i32 m0, s84, 0x2000
	s_nop 0
	global_load_lds_dwordx4 v190, s[8:9]
	v_lshl_add_u64 v[214:215], s[30:31], 0, v[196:197]
	s_mov_b32 m0, s35
	s_nop 0
	global_load_lds_dwordx4 v[214:215], off
	s_mov_b32 m0, s36
	s_nop 0
	global_load_lds_dwordx4 v[216:217], off
	s_waitcnt vmcnt(8)
	s_waitcnt lgkmcnt(0)
	s_barrier
	s_waitcnt lgkmcnt(0)
	v_mfma_f32_16x16x32_bf16 v[62:65], v[78:81], v[162:165], v[62:65]
	v_mfma_f32_16x16x32_bf16 v[58:61], v[102:105], v[162:165], v[58:61]
	v_mfma_f32_16x16x32_bf16 v[46:49], v[78:81], v[170:173], v[46:49]
	v_mfma_f32_16x16x32_bf16 v[42:45], v[102:105], v[170:173], v[42:45]
	v_mfma_f32_16x16x32_bf16 v[30:33], v[78:81], v[178:181], v[30:33]
	v_mfma_f32_16x16x32_bf16 v[26:29], v[102:105], v[178:181], v[26:29]
	v_mfma_f32_16x16x32_bf16 v[14:17], v[78:81], v[186:189], v[14:17]
	v_mfma_f32_16x16x32_bf16 v[10:13], v[102:105], v[186:189], v[10:13]
	v_mfma_f32_16x16x32_bf16 v[62:65], v[86:89], v[166:169], v[62:65]
	v_mfma_f32_16x16x32_bf16 v[58:61], v[110:113], v[166:169], v[58:61]
	v_mfma_f32_16x16x32_bf16 v[46:49], v[86:89], v[174:177], v[46:49]
	v_mfma_f32_16x16x32_bf16 v[42:45], v[110:113], v[174:177], v[42:45]
	v_mfma_f32_16x16x32_bf16 v[30:33], v[86:89], v[182:185], v[30:33]
	v_mfma_f32_16x16x32_bf16 v[26:29], v[110:113], v[182:185], v[26:29]
	v_mfma_f32_16x16x32_bf16 v[14:17], v[86:89], v[202:205], v[14:17]
	v_mfma_f32_16x16x32_bf16 v[10:13], v[110:113], v[202:205], v[10:13]
	v_mfma_f32_16x16x32_bf16 v[54:57], v[122:125], v[162:165], v[54:57]
	v_mfma_f32_16x16x32_bf16 v[50:53], v[146:149], v[162:165], v[50:53]
	v_mfma_f32_16x16x32_bf16 v[38:41], v[122:125], v[170:173], v[38:41]
	v_mfma_f32_16x16x32_bf16 v[34:37], v[146:149], v[170:173], v[34:37]
	v_mfma_f32_16x16x32_bf16 v[22:25], v[122:125], v[178:181], v[22:25]
	v_mfma_f32_16x16x32_bf16 v[18:21], v[146:149], v[178:181], v[18:21]
	v_mfma_f32_16x16x32_bf16 v[6:9], v[122:125], v[186:189], v[6:9]
	v_mfma_f32_16x16x32_bf16 v[2:5], v[146:149], v[186:189], v[2:5]
	v_mfma_f32_16x16x32_bf16 v[54:57], v[134:137], v[166:169], v[54:57]
	v_mfma_f32_16x16x32_bf16 v[50:53], v[150:153], v[166:169], v[50:53]
	v_mfma_f32_16x16x32_bf16 v[38:41], v[134:137], v[174:177], v[38:41]
	v_mfma_f32_16x16x32_bf16 v[34:37], v[150:153], v[174:177], v[34:37]
	v_mfma_f32_16x16x32_bf16 v[22:25], v[134:137], v[182:185], v[22:25]
	v_mfma_f32_16x16x32_bf16 v[18:21], v[150:153], v[182:185], v[18:21]
	v_mfma_f32_16x16x32_bf16 v[6:9], v[134:137], v[202:205], v[6:9]
	v_mfma_f32_16x16x32_bf16 v[2:5], v[150:153], v[202:205], v[2:5]
	s_barrier
; #define PG8_STAGE(bufoff, gbase, voff) do { _Pragma("unroll") for (int _i = 0; _i < 2; ++_i) \
;         __builtin_amdgcn_global_load_lds((const unsigned*)((const char*)(gbase) + (voff)[_i]), (PG8_LAS unsigned*)(lds + (bufoff) + ldsw + _i * 8192), 16, 0, 0); } while (0)
; #define PG8_LDA(dst, b, h) do { _Pragma("unroll") for (int m = 0; m < 4; ++m) _Pragma("unroll") for (int k = 0; k < 2; ++k) dst[m][k] = *(const PG8_LAS bf16x8*)(lds + PG8_SA(b, h) + aoff + m * 2048 + k * 1024); } while (0)
; #define PG8_LDB(dst, b, h) do { _Pragma("unroll") for (int n = 0; n < 2; ++n) _Pragma("unroll") for (int k = 0; k < 2; ++k) dst[n][k] = *(const PG8_LAS bf16x8*)(lds + PG8_SB(b, h) + boff + n * 2048 + k * 1024); } while (0)
; #define PG8_MMA(ai, bj, At, Bt) do { __builtin_amdgcn_s_setprio(1); _Pragma("unroll") for (int m = 0; m < 4; ++m) _Pragma("unroll") for (int n = 0; n < 2; ++n) _Pragma("unroll") for (int k = 0; k < 2; ++k) \
;         acc[ai][bj][m][n] = __builtin_amdgcn_mfma_f32_16x16x32_bf16(Bt[n][k], At[m][k], acc[ai][bj][m][n], 0, 0, 0); __builtin_amdgcn_s_setprio(0); } while (0)
; #define PG8_WAIT_V(n) asm volatile("s_waitcnt vmcnt(" #n ")" ::: "memory")
; #define PG8_WAIT_L(n) asm volatile("s_waitcnt lgkmcnt(" #n ")" ::: "memory")
; #define PG8_BAR __builtin_amdgcn_s_barrier()
; #define PG8_SCHED __builtin_amdgcn_sched_barrier(0)
; template <class Epi, class Sched, bool ALIGN_EPI = false, bool SP2 = false>
; __device__ __forceinline__ void gemm_phase(PG8_LAS unsigned char* lds, const Gemm g, const Sched& S, const Epi& E, int wave_s) {
;     ...
;             PG8_LDB(B0, 1, 0); PG8_LDB(B1, 1, 1); PG8_SCHED; PG8_LDA(At, 1, 0); PG8_STAGE(PG8_SA(0, 1), a2 + hstepA, voffA);
;             PG8_WAIT_V(8); PG8_WAIT_L(0); PG8_BAR; PG8_MMA(0, 0, At, B0); PG8_MMA(0, 1, At, B1); PG8_BAR; PG8_SCHED;
;             PG8_LDA(At, 1, 1); PG8_STAGE(PG8_SB(1, 0), b3, voffB); PG8_STAGE(PG8_SB(1, 1), b3 + hstepB, voffB); PG8_STAGE(PG8_SA(1, 0), a3, voffA);
;             PG8_WAIT_V(8); PG8_WAIT_L(0); PG8_BAR; PG8_MMA(1, 0, At, B0); PG8_MMA(1, 1, At, B1); PG8_BAR; PG8_SCHED;
	s_add_i32 s84, 0, 0x18000
	s_add_i32 s85, 0, 0x1c000
	ds_read_b128 v[78:81], v230
	ds_read_b128 v[86:89], v230 offset:1024
	ds_read_b128 v[102:105], v230 offset:2048
	ds_read_b128 v[110:113], v230 offset:3072
	ds_read_b128 v[122:125], v231
	ds_read_b128 v[134:137], v231 offset:1024
	ds_read_b128 v[146:149], v231 offset:2048
	ds_read_b128 v[150:153], v231 offset:3072
	s_add_u32 s8, s30, 0x160000
	s_addc_u32 s9, s31, 0
	s_mov_b32 m0, s37
	ds_read_b128 v[162:165], v212 offset:32768
	ds_read_b128 v[166:169], v212 offset:33792
	ds_read_b128 v[170:173], v212 offset:34816
	ds_read_b128 v[174:177], v212 offset:35840
	ds_read_b128 v[178:181], v212 offset:36864
	ds_read_b128 v[182:185], v212 offset:37888
	ds_read_b128 v[186:189], v212 offset:38912
	ds_read_b128 v[202:205], v212 offset:39936
	global_load_lds_dwordx4 v196, s[8:9]
	v_lshl_add_u64 v[218:219], s[8:9], 0, v[192:193]
	s_mov_b32 m0, s40
	s_nop 0
	global_load_lds_dwordx4 v[218:219], off
	s_waitcnt vmcnt(8)
	s_waitcnt lgkmcnt(0)
	s_barrier
	s_waitcnt lgkmcnt(0)
	v_mfma_f32_16x16x32_bf16 v[158:161], v[78:81], v[162:165], v[158:161]
	v_mfma_f32_16x16x32_bf16 v[154:157], v[102:105], v[162:165], v[154:157]
	v_mfma_f32_16x16x32_bf16 v[130:133], v[78:81], v[170:173], v[130:133]
	v_mfma_f32_16x16x32_bf16 v[126:129], v[102:105], v[170:173], v[126:129]
	v_mfma_f32_16x16x32_bf16 v[106:109], v[78:81], v[178:181], v[106:109]
	v_mfma_f32_16x16x32_bf16 v[98:101], v[102:105], v[178:181], v[98:101]
	v_mfma_f32_16x16x32_bf16 v[82:85], v[78:81], v[186:189], v[82:85]
	v_mfma_f32_16x16x32_bf16 v[74:77], v[102:105], v[186:189], v[74:77]
	v_mfma_f32_16x16x32_bf16 v[158:161], v[86:89], v[166:169], v[158:161]
	v_mfma_f32_16x16x32_bf16 v[154:157], v[110:113], v[166:169], v[154:157]
	v_mfma_f32_16x16x32_bf16 v[130:133], v[86:89], v[174:177], v[130:133]
	v_mfma_f32_16x16x32_bf16 v[126:129], v[110:113], v[174:177], v[126:129]
	v_mfma_f32_16x16x32_bf16 v[106:109], v[86:89], v[182:185], v[106:109]
	v_mfma_f32_16x16x32_bf16 v[98:101], v[110:113], v[182:185], v[98:101]
	v_mfma_f32_16x16x32_bf16 v[82:85], v[86:89], v[202:205], v[82:85]
	v_mfma_f32_16x16x32_bf16 v[74:77], v[110:113], v[202:205], v[74:77]
	v_mfma_f32_16x16x32_bf16 v[142:145], v[122:125], v[162:165], v[142:145]
	v_mfma_f32_16x16x32_bf16 v[138:141], v[146:149], v[162:165], v[138:141]
	v_mfma_f32_16x16x32_bf16 v[118:121], v[122:125], v[170:173], v[118:121]
	v_mfma_f32_16x16x32_bf16 v[114:117], v[146:149], v[170:173], v[114:117]
	v_mfma_f32_16x16x32_bf16 v[94:97], v[122:125], v[178:181], v[94:97]
	v_mfma_f32_16x16x32_bf16 v[90:93], v[146:149], v[178:181], v[90:93]
	v_mfma_f32_16x16x32_bf16 v[70:73], v[122:125], v[186:189], v[70:73]
	v_mfma_f32_16x16x32_bf16 v[66:69], v[146:149], v[186:189], v[66:69]
	v_mfma_f32_16x16x32_bf16 v[142:145], v[134:137], v[166:169], v[142:145]
	v_mfma_f32_16x16x32_bf16 v[138:141], v[150:153], v[166:169], v[138:141]
	v_mfma_f32_16x16x32_bf16 v[118:121], v[134:137], v[174:177], v[118:121]
	v_mfma_f32_16x16x32_bf16 v[114:117], v[150:153], v[174:177], v[114:117]
	v_mfma_f32_16x16x32_bf16 v[94:97], v[134:137], v[182:185], v[94:97]
	v_mfma_f32_16x16x32_bf16 v[90:93], v[150:153], v[182:185], v[90:93]
	v_mfma_f32_16x16x32_bf16 v[70:73], v[134:137], v[202:205], v[70:73]
	v_mfma_f32_16x16x32_bf16 v[66:69], v[150:153], v[202:205], v[66:69]
	s_barrier
	s_add_i32 s8, s84, s22
	v_lshl_add_u64 v[206:207], v[206:207], 0, s[60:61]
	s_mov_b32 m0, s8
	ds_read_b128 v[162:165], v212 offset:49152
	ds_read_b128 v[166:169], v212 offset:50176
	ds_read_b128 v[170:173], v212 offset:51200
	ds_read_b128 v[174:177], v212 offset:52224
	ds_read_b128 v[178:181], v212 offset:53248
	ds_read_b128 v[182:185], v212 offset:54272
	ds_read_b128 v[186:189], v212 offset:55296
	ds_read_b128 v[202:205], v212 offset:56320
	global_load_lds_dwordx4 v[206:207], off
	s_add_i32 m0, s8, 0x2000
	s_add_u32 s6, s6, 0x160080
	v_lshl_add_u64 v[206:207], v[208:209], 0, s[60:61]
	s_addc_u32 s7, s7, 0
	s_add_i32 s8, s85, s22
	global_load_lds_dwordx4 v[206:207], off
	s_mov_b32 m0, s8
	s_nop 0
	global_load_lds_dwordx4 v194, s[6:7]
	s_add_i32 m0, s8, 0x2000
	s_nop 0
	global_load_lds_dwordx4 v190, s[6:7]
	v_lshl_add_u64 v[206:207], v[214:215], 0, s[60:61]
	s_mov_b32 m0, s44
	s_nop 0
	global_load_lds_dwordx4 v[206:207], off
	v_lshl_add_u64 v[206:207], v[216:217], 0, s[60:61]
	s_mov_b32 m0, s45
	s_nop 0
	global_load_lds_dwordx4 v[206:207], off
	s_waitcnt vmcnt(8)
	s_waitcnt lgkmcnt(0)
	s_barrier
	s_waitcnt lgkmcnt(0)
	v_mfma_f32_16x16x32_bf16 v[62:65], v[78:81], v[162:165], v[62:65]
	v_mfma_f32_16x16x32_bf16 v[58:61], v[102:105], v[162:165], v[58:61]
	v_mfma_f32_16x16x32_bf16 v[46:49], v[78:81], v[170:173], v[46:49]
	v_mfma_f32_16x16x32_bf16 v[42:45], v[102:105], v[170:173], v[42:45]
	v_mfma_f32_16x16x32_bf16 v[30:33], v[78:81], v[178:181], v[30:33]
	v_mfma_f32_16x16x32_bf16 v[26:29], v[102:105], v[178:181], v[26:29]
	v_mfma_f32_16x16x32_bf16 v[14:17], v[78:81], v[186:189], v[14:17]
	v_mfma_f32_16x16x32_bf16 v[10:13], v[102:105], v[186:189], v[10:13]
	v_mfma_f32_16x16x32_bf16 v[62:65], v[86:89], v[166:169], v[62:65]
	v_mfma_f32_16x16x32_bf16 v[58:61], v[110:113], v[166:169], v[58:61]
	v_mfma_f32_16x16x32_bf16 v[46:49], v[86:89], v[174:177], v[46:49]
	v_mfma_f32_16x16x32_bf16 v[42:45], v[110:113], v[174:177], v[42:45]
	v_mfma_f32_16x16x32_bf16 v[30:33], v[86:89], v[182:185], v[30:33]
	v_mfma_f32_16x16x32_bf16 v[26:29], v[110:113], v[182:185], v[26:29]
	v_mfma_f32_16x16x32_bf16 v[14:17], v[86:89], v[202:205], v[14:17]
	v_mfma_f32_16x16x32_bf16 v[10:13], v[110:113], v[202:205], v[10:13]
	v_mfma_f32_16x16x32_bf16 v[54:57], v[122:125], v[162:165], v[54:57]
	v_mfma_f32_16x16x32_bf16 v[50:53], v[146:149], v[162:165], v[50:53]
	v_mfma_f32_16x16x32_bf16 v[38:41], v[122:125], v[170:173], v[38:41]
	v_mfma_f32_16x16x32_bf16 v[34:37], v[146:149], v[170:173], v[34:37]
	v_mfma_f32_16x16x32_bf16 v[22:25], v[122:125], v[178:181], v[22:25]
	v_mfma_f32_16x16x32_bf16 v[18:21], v[146:149], v[178:181], v[18:21]
	v_mfma_f32_16x16x32_bf16 v[6:9], v[122:125], v[186:189], v[6:9]
	v_mfma_f32_16x16x32_bf16 v[2:5], v[146:149], v[186:189], v[2:5]
	v_mfma_f32_16x16x32_bf16 v[54:57], v[134:137], v[166:169], v[54:57]
	v_mfma_f32_16x16x32_bf16 v[50:53], v[150:153], v[166:169], v[50:53]
	v_mfma_f32_16x16x32_bf16 v[38:41], v[134:137], v[174:177], v[38:41]
	v_mfma_f32_16x16x32_bf16 v[34:37], v[150:153], v[174:177], v[34:37]
	v_mfma_f32_16x16x32_bf16 v[22:25], v[134:137], v[182:185], v[22:25]
	v_mfma_f32_16x16x32_bf16 v[18:21], v[150:153], v[182:185], v[18:21]
	v_mfma_f32_16x16x32_bf16 v[6:9], v[134:137], v[202:205], v[6:9]
	v_mfma_f32_16x16x32_bf16 v[2:5], v[150:153], v[202:205], v[2:5]
	s_barrier
	s_add_i32 s81, s81, 2
	s_add_u32 s2, s2, 0x100
	s_addc_u32 s3, s3, 0
	s_cmpk_gt_u32 s81, 0x55
	s_mov_b64 s[8:9], s[4:5]
	s_cbranch_scc0 .LBB0_786
	s_and_b64 vcc, exec, s[88:89]
	s_cbranch_vccz .LBB0_789
	s_barrier
